# v60 plus accumulator zeroing at GEMM unit starts with v_pk_mov_b32 (one packed move per register pair)
# speedup vs baseline: 1.0074x; 1.0042x over previous
; template <class Epi, class Sched, bool ALIGN_EPI = false, bool SP2 = false>
; __device__ __forceinline__ void gemm_phase(PG8_LAS unsigned char* lds, const Gemm g, const Sched& S, const Epi& E, int tid_in) {
;     ...
;         const char* nA = has_next ? (const char*)g.A + (size_t)nxt.pm * tstep : cA; const char* nB = has_next ? (const char*)g.Bt + (size_t)nxt.pn * tstep : cB;
;         for (int t = 0; t < nt; t += 2) {
;             const bool last = (t == nt - 2);
;             const char* a1 = cA + (size_t)(t + 1) * kstep;
;             const char* a2 = last ? nA : cA + (size_t)(t + 2) * kstep; const char* b2 = last ? nB : cB + (size_t)(t + 2) * kstep;
;             const char* a3 = a2 + kstep; const char* b3 = b2 + kstep;
;             if (last && has_next) S.a_ready(nxt);
;             if constexpr (SP2) {
;             PG8_LDB(B0, 0, 0); PG8_LDB(B1, 0, 1); PG8_SCHED; PG8_LDA(At, 0, 0); PG8_STAGE(PG8_SA(1, 1), a1 + hstep, voffA);
;             PG8_WAIT_V(8); PG8_WAIT_L(0); PG8_BAR; PG8_MMA(0, 0, At, B0); PG8_MMA(0, 1, At, B1); PG8_BAR; PG8_SCHED;
;             PG8_LDA(At, 0, 1); PG8_STAGE(PG8_SB(0, 0), b2, voffB); PG8_STAGE(PG8_SB(0, 1), b2 + hstep, voffB); PG8_STAGE(PG8_SA(0, 0), a2, voffA);
;             PG8_WAIT_V(8); PG8_WAIT_L(0); PG8_BAR; PG8_MMA(1, 0, At, B0); PG8_MMA(1, 1, At, B1); PG8_BAR; PG8_SCHED;
;             PG8_LDB(B0, 1, 0); PG8_LDB(B1, 1, 1); PG8_SCHED; PG8_LDA(At, 1, 0); PG8_STAGE(PG8_SA(0, 1), a2 + hstep, voffA);
;             PG8_WAIT_V(8); PG8_WAIT_L(0); PG8_BAR; PG8_MMA(0, 0, At, B0); PG8_MMA(0, 1, At, B1); PG8_BAR; PG8_SCHED;
;             PG8_LDA(At, 1, 1); PG8_STAGE(PG8_SB(1, 0), b3, voffB); PG8_STAGE(PG8_SB(1, 1), b3 + hstep, voffB); PG8_STAGE(PG8_SA(1, 0), a3, voffA);
;             PG8_WAIT_V(8); PG8_WAIT_L(0); PG8_BAR; PG8_MMA(1, 0, At, B0); PG8_MMA(1, 1, At, B1); PG8_BAR; PG8_SCHED;
;             } else {
;             PG8_LDB(B0, 0, 0); PG8_SCHED; PG8_LDA(At, 0, 0); PG8_STAGE(PG8_SA(1, 1), a1 + hstep, voffA);
;             PG8_WAIT_L(8); PG8_BAR; PG8_WAIT_L(0); PG8_MMA(0, 0, At, B0); PG8_BAR; PG8_SCHED;
;             PG8_LDB(B1, 0, 1); PG8_STAGE(PG8_SB(0, 0), b2, voffB);
;             PG8_BAR; PG8_WAIT_L(0); PG8_MMA(0, 1, At, B1); PG8_BAR;
;             PG8_LDA(At, 0, 1); PG8_STAGE(PG8_SA(0, 0), a2, voffA);
;             PG8_BAR; PG8_WAIT_L(0); PG8_MMA(1, 0, At, B0); PG8_BAR; PG8_SCHED;
.LBB0_119:
	s_ashr_i32 s11, s10, 31
	s_lshl_b64 s[22:23], s[10:11], 19
	s_add_u32 s22, s6, s22
	s_addc_u32 s23, s7, s23
	s_and_b64 s[24:25], s[4:5], exec
	s_cselect_b32 s11, s23, s35
	s_cselect_b32 s37, s22, s34
	s_ashr_i32 s9, s8, 31
	s_lshl_b64 s[24:25], s[8:9], 19
	s_add_u32 s24, s1, s24
	s_addc_u32 s25, s3, s25
	s_and_b64 s[40:41], s[4:5], exec
	s_cselect_b32 s9, s25, s27
	s_cselect_b32 s39, s24, s26
	s_add_u32 s42, s26, 0x100
	s_addc_u32 s43, s27, 0
	s_add_u32 s26, s34, 0x40080
	v_mov_b32_e32 v0, 0
	v_mov_b32_e32 v1, v0
	s_addc_u32 s27, s35, 0
	s_mov_b32 s57, -2
	v_pk_mov_b32 v[2:3], v[0:1], v[0:1]
	v_pk_mov_b32 v[4:5], v[0:1], v[0:1]
	v_pk_mov_b32 v[6:7], v[0:1], v[0:1]
	v_pk_mov_b32 v[16:17], v[0:1], v[0:1]
	v_pk_mov_b32 v[18:19], v[0:1], v[0:1]
	v_pk_mov_b32 v[20:21], v[0:1], v[0:1]
	v_pk_mov_b32 v[22:23], v[0:1], v[0:1]
	v_pk_mov_b32 v[32:33], v[0:1], v[0:1]
	v_pk_mov_b32 v[34:35], v[0:1], v[0:1]
	v_pk_mov_b32 v[36:37], v[0:1], v[0:1]
	v_pk_mov_b32 v[38:39], v[0:1], v[0:1]
	v_pk_mov_b32 v[48:49], v[0:1], v[0:1]
	v_pk_mov_b32 v[50:51], v[0:1], v[0:1]
	v_pk_mov_b32 v[52:53], v[0:1], v[0:1]
	v_pk_mov_b32 v[54:55], v[0:1], v[0:1]
	v_pk_mov_b32 v[8:9], v[0:1], v[0:1]
	v_pk_mov_b32 v[10:11], v[0:1], v[0:1]
	v_pk_mov_b32 v[12:13], v[0:1], v[0:1]
	v_pk_mov_b32 v[14:15], v[0:1], v[0:1]
	v_pk_mov_b32 v[24:25], v[0:1], v[0:1]
	v_pk_mov_b32 v[26:27], v[0:1], v[0:1]
	v_pk_mov_b32 v[28:29], v[0:1], v[0:1]
	v_pk_mov_b32 v[30:31], v[0:1], v[0:1]
	v_pk_mov_b32 v[40:41], v[0:1], v[0:1]
	v_pk_mov_b32 v[42:43], v[0:1], v[0:1]
	v_pk_mov_b32 v[44:45], v[0:1], v[0:1]
	v_pk_mov_b32 v[46:47], v[0:1], v[0:1]
	v_pk_mov_b32 v[56:57], v[0:1], v[0:1]
	v_pk_mov_b32 v[58:59], v[0:1], v[0:1]
	v_pk_mov_b32 v[60:61], v[0:1], v[0:1]
	v_pk_mov_b32 v[62:63], v[0:1], v[0:1]
	v_pk_mov_b32 v[64:65], v[0:1], v[0:1]
	v_pk_mov_b32 v[66:67], v[0:1], v[0:1]
	v_pk_mov_b32 v[68:69], v[0:1], v[0:1]
	v_pk_mov_b32 v[70:71], v[0:1], v[0:1]
	v_pk_mov_b32 v[80:81], v[0:1], v[0:1]
	v_pk_mov_b32 v[82:83], v[0:1], v[0:1]
	v_pk_mov_b32 v[84:85], v[0:1], v[0:1]
	v_pk_mov_b32 v[86:87], v[0:1], v[0:1]
	v_pk_mov_b32 v[96:97], v[0:1], v[0:1]
	v_pk_mov_b32 v[98:99], v[0:1], v[0:1]
	v_pk_mov_b32 v[100:101], v[0:1], v[0:1]
	v_pk_mov_b32 v[102:103], v[0:1], v[0:1]
	v_pk_mov_b32 v[112:113], v[0:1], v[0:1]
	v_pk_mov_b32 v[114:115], v[0:1], v[0:1]
	v_pk_mov_b32 v[116:117], v[0:1], v[0:1]
	v_pk_mov_b32 v[118:119], v[0:1], v[0:1]
	v_pk_mov_b32 v[72:73], v[0:1], v[0:1]
	v_pk_mov_b32 v[74:75], v[0:1], v[0:1]
	v_pk_mov_b32 v[76:77], v[0:1], v[0:1]
	v_pk_mov_b32 v[78:79], v[0:1], v[0:1]
	v_pk_mov_b32 v[88:89], v[0:1], v[0:1]
	v_pk_mov_b32 v[90:91], v[0:1], v[0:1]
	v_pk_mov_b32 v[92:93], v[0:1], v[0:1]
	v_pk_mov_b32 v[94:95], v[0:1], v[0:1]
	v_pk_mov_b32 v[104:105], v[0:1], v[0:1]
	v_pk_mov_b32 v[106:107], v[0:1], v[0:1]
	v_pk_mov_b32 v[108:109], v[0:1], v[0:1]
	v_pk_mov_b32 v[110:111], v[0:1], v[0:1]
	v_pk_mov_b32 v[120:121], v[0:1], v[0:1]
	v_pk_mov_b32 v[122:123], v[0:1], v[0:1]
	v_pk_mov_b32 v[124:125], v[0:1], v[0:1]
	v_pk_mov_b32 v[126:127], v[0:1], v[0:1]
	v_readlane_b32 s98, v252, 5
	s_nop 1
	s_lshl_b32 s98, s98, 5
	s_add_i32 m0, s98, 0x20080
	s_lshl_b32 s98, s38, 14
	s_add_u32 s98, s100, s98
	s_addc_u32 s99, s101, 0
	global_load_lds_dwordx4 v238, s[98:99]
	global_load_lds_dwordx4 v238, s[98:99] offset:1024

; template <class Epi, class Sched, bool ALIGN_EPI = false, bool SP2 = false>
; __device__ __forceinline__ void gemm_phase(PG8_LAS unsigned char* lds, const Gemm g, const Sched& S, const Epi& E, int tid_in) {
;     ...
;         const char* nA = has_next ? (const char*)g.A + (size_t)nxt.pm * tstep : cA; const char* nB = has_next ? (const char*)g.Bt + (size_t)nxt.pn * tstep : cB;
;         for (int t = 0; t < nt; t += 2) {
;             const bool last = (t == nt - 2);
;             const char* a1 = cA + (size_t)(t + 1) * kstep;
;             const char* a2 = last ? nA : cA + (size_t)(t + 2) * kstep; const char* b2 = last ? nB : cB + (size_t)(t + 2) * kstep;
;             const char* a3 = a2 + kstep; const char* b3 = b2 + kstep;
;             if (last && has_next) S.a_ready(nxt);
;             if constexpr (SP2) {
;             PG8_LDB(B0, 0, 0); PG8_LDB(B1, 0, 1); PG8_SCHED; PG8_LDA(At, 0, 0); PG8_STAGE(PG8_SA(1, 1), a1 + hstep, voffA);
;             PG8_WAIT_V(8); PG8_WAIT_L(0); PG8_BAR; PG8_MMA(0, 0, At, B0); PG8_MMA(0, 1, At, B1); PG8_BAR; PG8_SCHED;
;             PG8_LDA(At, 0, 1); PG8_STAGE(PG8_SB(0, 0), b2, voffB); PG8_STAGE(PG8_SB(0, 1), b2 + hstep, voffB); PG8_STAGE(PG8_SA(0, 0), a2, voffA);
;             PG8_WAIT_V(8); PG8_WAIT_L(0); PG8_BAR; PG8_MMA(1, 0, At, B0); PG8_MMA(1, 1, At, B1); PG8_BAR; PG8_SCHED;
;             PG8_LDB(B0, 1, 0); PG8_LDB(B1, 1, 1); PG8_SCHED; PG8_LDA(At, 1, 0); PG8_STAGE(PG8_SA(0, 1), a2 + hstep, voffA);
;             PG8_WAIT_V(8); PG8_WAIT_L(0); PG8_BAR; PG8_MMA(0, 0, At, B0); PG8_MMA(0, 1, At, B1); PG8_BAR; PG8_SCHED;
;             PG8_LDA(At, 1, 1); PG8_STAGE(PG8_SB(1, 0), b3, voffB); PG8_STAGE(PG8_SB(1, 1), b3 + hstep, voffB); PG8_STAGE(PG8_SA(1, 0), a3, voffA);
;             PG8_WAIT_V(8); PG8_WAIT_L(0); PG8_BAR; PG8_MMA(1, 0, At, B0); PG8_MMA(1, 1, At, B1); PG8_BAR; PG8_SCHED;
;             } else {
;             PG8_LDB(B0, 0, 0); PG8_SCHED; PG8_LDA(At, 0, 0); PG8_STAGE(PG8_SA(1, 1), a1 + hstep, voffA);
;             PG8_WAIT_L(8); PG8_BAR; PG8_WAIT_L(0); PG8_MMA(0, 0, At, B0); PG8_BAR; PG8_SCHED;
;             PG8_LDB(B1, 0, 1); PG8_STAGE(PG8_SB(0, 0), b2, voffB);
;             PG8_BAR; PG8_WAIT_L(0); PG8_MMA(0, 1, At, B1); PG8_BAR;
;             PG8_LDA(At, 0, 1); PG8_STAGE(PG8_SA(0, 0), a2, voffA);
;             PG8_BAR; PG8_WAIT_L(0); PG8_MMA(1, 0, At, B0); PG8_BAR; PG8_SCHED;
.LBB0_435:
	s_ashr_i32 s37, s36, 31
	s_lshl_b64 s[38:39], s[36:37], 19
	s_add_u32 s38, s1, s38
	s_addc_u32 s39, s3, s39
	s_and_b64 s[40:41], s[12:13], exec
	s_cselect_b32 s37, s39, s47
	s_cselect_b32 s43, s38, s46
	s_ashr_i32 s35, s34, 31
	s_lshl_b64 s[40:41], s[34:35], 19
	s_add_u32 s40, s4, s40
	s_addc_u32 s41, s5, s41
	s_and_b64 s[48:49], s[12:13], exec
	s_cselect_b32 s35, s41, s45
	s_cselect_b32 s61, s40, s44
	s_add_u32 s62, s44, 0x100
	s_addc_u32 s63, s45, 0
	s_add_u32 s44, s46, 0x40080
	v_mov_b32_e32 v0, 0
	v_mov_b32_e32 v1, v0
	s_addc_u32 s45, s47, 0
	s_mov_b32 s64, -2
	s_waitcnt lgkmcnt(0)
	v_pk_mov_b32 v[2:3], v[0:1], v[0:1]
	v_pk_mov_b32 v[4:5], v[0:1], v[0:1]
	v_pk_mov_b32 v[6:7], v[0:1], v[0:1]
	v_pk_mov_b32 v[16:17], v[0:1], v[0:1]
	v_pk_mov_b32 v[18:19], v[0:1], v[0:1]
	v_pk_mov_b32 v[20:21], v[0:1], v[0:1]
	v_pk_mov_b32 v[22:23], v[0:1], v[0:1]
	v_pk_mov_b32 v[32:33], v[0:1], v[0:1]
	v_pk_mov_b32 v[34:35], v[0:1], v[0:1]
	v_pk_mov_b32 v[36:37], v[0:1], v[0:1]
	v_pk_mov_b32 v[38:39], v[0:1], v[0:1]
	v_pk_mov_b32 v[48:49], v[0:1], v[0:1]
	v_pk_mov_b32 v[50:51], v[0:1], v[0:1]
	v_pk_mov_b32 v[52:53], v[0:1], v[0:1]
	v_pk_mov_b32 v[54:55], v[0:1], v[0:1]
	v_pk_mov_b32 v[8:9], v[0:1], v[0:1]
	v_pk_mov_b32 v[10:11], v[0:1], v[0:1]
	v_pk_mov_b32 v[12:13], v[0:1], v[0:1]
	v_pk_mov_b32 v[14:15], v[0:1], v[0:1]
	v_pk_mov_b32 v[24:25], v[0:1], v[0:1]
	v_pk_mov_b32 v[26:27], v[0:1], v[0:1]
	v_pk_mov_b32 v[28:29], v[0:1], v[0:1]
	v_pk_mov_b32 v[30:31], v[0:1], v[0:1]
	v_pk_mov_b32 v[40:41], v[0:1], v[0:1]
	v_pk_mov_b32 v[42:43], v[0:1], v[0:1]
	v_pk_mov_b32 v[44:45], v[0:1], v[0:1]
	v_pk_mov_b32 v[46:47], v[0:1], v[0:1]
	v_pk_mov_b32 v[56:57], v[0:1], v[0:1]
	v_pk_mov_b32 v[58:59], v[0:1], v[0:1]
	v_pk_mov_b32 v[60:61], v[0:1], v[0:1]
	v_pk_mov_b32 v[62:63], v[0:1], v[0:1]
	v_pk_mov_b32 v[64:65], v[0:1], v[0:1]
	v_pk_mov_b32 v[66:67], v[0:1], v[0:1]
	v_pk_mov_b32 v[68:69], v[0:1], v[0:1]
	v_pk_mov_b32 v[70:71], v[0:1], v[0:1]
	v_pk_mov_b32 v[80:81], v[0:1], v[0:1]
	v_pk_mov_b32 v[82:83], v[0:1], v[0:1]
	v_pk_mov_b32 v[84:85], v[0:1], v[0:1]
	v_pk_mov_b32 v[86:87], v[0:1], v[0:1]
	v_pk_mov_b32 v[96:97], v[0:1], v[0:1]
	v_pk_mov_b32 v[98:99], v[0:1], v[0:1]
	v_pk_mov_b32 v[100:101], v[0:1], v[0:1]
	v_pk_mov_b32 v[102:103], v[0:1], v[0:1]
	v_pk_mov_b32 v[112:113], v[0:1], v[0:1]
	v_pk_mov_b32 v[114:115], v[0:1], v[0:1]
	v_pk_mov_b32 v[116:117], v[0:1], v[0:1]
	v_pk_mov_b32 v[118:119], v[0:1], v[0:1]
	v_pk_mov_b32 v[72:73], v[0:1], v[0:1]
	v_pk_mov_b32 v[74:75], v[0:1], v[0:1]
	v_pk_mov_b32 v[76:77], v[0:1], v[0:1]
	v_pk_mov_b32 v[78:79], v[0:1], v[0:1]
	v_pk_mov_b32 v[88:89], v[0:1], v[0:1]
	v_pk_mov_b32 v[90:91], v[0:1], v[0:1]
	v_pk_mov_b32 v[92:93], v[0:1], v[0:1]
	v_pk_mov_b32 v[94:95], v[0:1], v[0:1]
	v_pk_mov_b32 v[104:105], v[0:1], v[0:1]
	v_pk_mov_b32 v[106:107], v[0:1], v[0:1]
	v_pk_mov_b32 v[108:109], v[0:1], v[0:1]
	v_pk_mov_b32 v[110:111], v[0:1], v[0:1]
	v_pk_mov_b32 v[120:121], v[0:1], v[0:1]
	v_pk_mov_b32 v[122:123], v[0:1], v[0:1]
	v_pk_mov_b32 v[124:125], v[0:1], v[0:1]
	v_pk_mov_b32 v[126:127], v[0:1], v[0:1]

; template <class Epi, class Sched, bool ALIGN_EPI = false, bool SP2 = false>
; __device__ __forceinline__ void gemm_phase(PG8_LAS unsigned char* lds, const Gemm g, const Sched& S, const Epi& E, int tid_in) {
;     ...
;         const char* nA = has_next ? (const char*)g.A + (size_t)nxt.pm * tstep : cA; const char* nB = has_next ? (const char*)g.Bt + (size_t)nxt.pn * tstep : cB;
;         for (int t = 0; t < nt; t += 2) {
;             const bool last = (t == nt - 2);
;             const char* a1 = cA + (size_t)(t + 1) * kstep;
;             const char* a2 = last ? nA : cA + (size_t)(t + 2) * kstep; const char* b2 = last ? nB : cB + (size_t)(t + 2) * kstep;
;             const char* a3 = a2 + kstep; const char* b3 = b2 + kstep;
;             if (last && has_next) S.a_ready(nxt);
;             if constexpr (SP2) {
;             PG8_LDB(B0, 0, 0); PG8_LDB(B1, 0, 1); PG8_SCHED; PG8_LDA(At, 0, 0); PG8_STAGE(PG8_SA(1, 1), a1 + hstep, voffA);
;             PG8_WAIT_V(8); PG8_WAIT_L(0); PG8_BAR; PG8_MMA(0, 0, At, B0); PG8_MMA(0, 1, At, B1); PG8_BAR; PG8_SCHED;
;             PG8_LDA(At, 0, 1); PG8_STAGE(PG8_SB(0, 0), b2, voffB); PG8_STAGE(PG8_SB(0, 1), b2 + hstep, voffB); PG8_STAGE(PG8_SA(0, 0), a2, voffA);
;             PG8_WAIT_V(8); PG8_WAIT_L(0); PG8_BAR; PG8_MMA(1, 0, At, B0); PG8_MMA(1, 1, At, B1); PG8_BAR; PG8_SCHED;
;             PG8_LDB(B0, 1, 0); PG8_LDB(B1, 1, 1); PG8_SCHED; PG8_LDA(At, 1, 0); PG8_STAGE(PG8_SA(0, 1), a2 + hstep, voffA);
;             PG8_WAIT_V(8); PG8_WAIT_L(0); PG8_BAR; PG8_MMA(0, 0, At, B0); PG8_MMA(0, 1, At, B1); PG8_BAR; PG8_SCHED;
;             PG8_LDA(At, 1, 1); PG8_STAGE(PG8_SB(1, 0), b3, voffB); PG8_STAGE(PG8_SB(1, 1), b3 + hstep, voffB); PG8_STAGE(PG8_SA(1, 0), a3, voffA);
;             PG8_WAIT_V(8); PG8_WAIT_L(0); PG8_BAR; PG8_MMA(1, 0, At, B0); PG8_MMA(1, 1, At, B1); PG8_BAR; PG8_SCHED;
;             } else {
;             PG8_LDB(B0, 0, 0); PG8_SCHED; PG8_LDA(At, 0, 0); PG8_STAGE(PG8_SA(1, 1), a1 + hstep, voffA);
;             PG8_WAIT_L(8); PG8_BAR; PG8_WAIT_L(0); PG8_MMA(0, 0, At, B0); PG8_BAR; PG8_SCHED;
;             PG8_LDB(B1, 0, 1); PG8_STAGE(PG8_SB(0, 0), b2, voffB);
;             PG8_BAR; PG8_WAIT_L(0); PG8_MMA(0, 1, At, B1); PG8_BAR;
;             PG8_LDA(At, 0, 1); PG8_STAGE(PG8_SA(0, 0), a2, voffA);
;             PG8_BAR; PG8_WAIT_L(0); PG8_MMA(1, 0, At, B0); PG8_BAR; PG8_SCHED;
.LBB0_519:
	s_ashr_i32 s25, s24, 31
	s_lshl_b64 s[26:27], s[24:25], 19
	s_add_u32 s26, s1, s26
	s_addc_u32 s27, s3, s27
	s_and_b64 s[34:35], s[10:11], exec
	s_cselect_b32 s25, s27, s41
	s_cselect_b32 s58, s26, s40
	s_ashr_i32 s23, s22, 31
	s_lshl_b64 s[34:35], s[22:23], 19
	s_add_u32 s34, s4, s34
	s_addc_u32 s35, s5, s35
	s_and_b64 s[44:45], s[10:11], exec
	s_cselect_b32 s23, s35, s39
	s_cselect_b32 s59, s34, s38
	s_add_u32 s60, s38, 0x100
	s_addc_u32 s61, s39, 0
	s_add_u32 s38, s40, 0x40080
	v_mov_b32_e32 v0, 0
	v_mov_b32_e32 v1, v0
	s_addc_u32 s39, s41, 0
	s_mov_b32 s62, -2
	v_pk_mov_b32 v[2:3], v[0:1], v[0:1]
	v_pk_mov_b32 v[4:5], v[0:1], v[0:1]
	v_pk_mov_b32 v[6:7], v[0:1], v[0:1]
	v_pk_mov_b32 v[16:17], v[0:1], v[0:1]
	v_pk_mov_b32 v[18:19], v[0:1], v[0:1]
	v_pk_mov_b32 v[20:21], v[0:1], v[0:1]
	v_pk_mov_b32 v[22:23], v[0:1], v[0:1]
	v_pk_mov_b32 v[32:33], v[0:1], v[0:1]
	v_pk_mov_b32 v[34:35], v[0:1], v[0:1]
	v_pk_mov_b32 v[36:37], v[0:1], v[0:1]
	v_pk_mov_b32 v[38:39], v[0:1], v[0:1]
	v_pk_mov_b32 v[48:49], v[0:1], v[0:1]
	v_pk_mov_b32 v[50:51], v[0:1], v[0:1]
	v_pk_mov_b32 v[52:53], v[0:1], v[0:1]
	v_pk_mov_b32 v[54:55], v[0:1], v[0:1]
	v_pk_mov_b32 v[8:9], v[0:1], v[0:1]
	v_pk_mov_b32 v[10:11], v[0:1], v[0:1]
	v_pk_mov_b32 v[12:13], v[0:1], v[0:1]
	v_pk_mov_b32 v[14:15], v[0:1], v[0:1]
	v_pk_mov_b32 v[24:25], v[0:1], v[0:1]
	v_pk_mov_b32 v[26:27], v[0:1], v[0:1]
	v_pk_mov_b32 v[28:29], v[0:1], v[0:1]
	v_pk_mov_b32 v[30:31], v[0:1], v[0:1]
	v_pk_mov_b32 v[40:41], v[0:1], v[0:1]
	v_pk_mov_b32 v[42:43], v[0:1], v[0:1]
	v_pk_mov_b32 v[44:45], v[0:1], v[0:1]
	v_pk_mov_b32 v[46:47], v[0:1], v[0:1]
	v_pk_mov_b32 v[56:57], v[0:1], v[0:1]
	v_pk_mov_b32 v[58:59], v[0:1], v[0:1]
	v_pk_mov_b32 v[60:61], v[0:1], v[0:1]
	v_pk_mov_b32 v[62:63], v[0:1], v[0:1]
	v_pk_mov_b32 v[64:65], v[0:1], v[0:1]
	v_pk_mov_b32 v[66:67], v[0:1], v[0:1]
	v_pk_mov_b32 v[68:69], v[0:1], v[0:1]
	v_pk_mov_b32 v[70:71], v[0:1], v[0:1]
	v_pk_mov_b32 v[80:81], v[0:1], v[0:1]
	v_pk_mov_b32 v[82:83], v[0:1], v[0:1]
	v_pk_mov_b32 v[84:85], v[0:1], v[0:1]
	v_pk_mov_b32 v[86:87], v[0:1], v[0:1]
	v_pk_mov_b32 v[96:97], v[0:1], v[0:1]
	v_pk_mov_b32 v[98:99], v[0:1], v[0:1]
	v_pk_mov_b32 v[100:101], v[0:1], v[0:1]
	v_pk_mov_b32 v[102:103], v[0:1], v[0:1]
	v_pk_mov_b32 v[112:113], v[0:1], v[0:1]
	v_pk_mov_b32 v[114:115], v[0:1], v[0:1]
	v_pk_mov_b32 v[116:117], v[0:1], v[0:1]
	v_pk_mov_b32 v[118:119], v[0:1], v[0:1]
	v_pk_mov_b32 v[72:73], v[0:1], v[0:1]
	v_pk_mov_b32 v[74:75], v[0:1], v[0:1]
	v_pk_mov_b32 v[76:77], v[0:1], v[0:1]
	v_pk_mov_b32 v[78:79], v[0:1], v[0:1]
	v_pk_mov_b32 v[88:89], v[0:1], v[0:1]
	v_pk_mov_b32 v[90:91], v[0:1], v[0:1]
	v_pk_mov_b32 v[92:93], v[0:1], v[0:1]
	v_pk_mov_b32 v[94:95], v[0:1], v[0:1]
	v_pk_mov_b32 v[104:105], v[0:1], v[0:1]
	v_pk_mov_b32 v[106:107], v[0:1], v[0:1]
	v_pk_mov_b32 v[108:109], v[0:1], v[0:1]
	v_pk_mov_b32 v[110:111], v[0:1], v[0:1]
	v_pk_mov_b32 v[120:121], v[0:1], v[0:1]
	v_pk_mov_b32 v[122:123], v[0:1], v[0:1]
	v_pk_mov_b32 v[124:125], v[0:1], v[0:1]
	v_pk_mov_b32 v[126:127], v[0:1], v[0:1]
	v_readlane_b32 s98, v252, 5
	s_nop 1
	s_lshl_b32 s98, s98, 5
	s_add_i32 m0, s98, 0x20080
	s_lshl_b32 s98, s36, 14
	s_add_u32 s98, s100, s98
	s_addc_u32 s99, s101, 0
	global_load_lds_dwordx4 v238, s[98:99]
	global_load_lds_dwordx4 v238, s[98:99] offset:1024

; template <class Epi, class Sched, bool ALIGN_EPI = false, bool SP2 = false>
; __device__ __forceinline__ void gemm_phase(PG8_LAS unsigned char* lds, const Gemm g, const Sched& S, const Epi& E, int tid_in) {
;     ...
; #pragma unroll
;         for (int a = 0; a < 2; ++a)
; #pragma unroll
;             for (int b = 0; b < 2; ++b)
; #pragma unroll
;                 for (int m = 0; m < 4; ++m)
; #pragma unroll
;                     for (int n = 0; n < 2; ++n) acc[a][b][m][n] = (f32x4){0.f, 0.f, 0.f, 0.f};
;         cur = nxt; cA = nA; cB = nB; ++ui;
.LBB0_601:
	s_add_u32 s62, s40, 0x100
	v_mov_b32_e32 v0, 0
	v_mov_b32_e32 v1, v0
	s_addc_u32 s63, s41, 0
	s_mov_b32 s64, -2
	s_waitcnt lgkmcnt(0)
	v_pk_mov_b32 v[2:3], v[0:1], v[0:1]
	v_pk_mov_b32 v[4:5], v[0:1], v[0:1]
	v_pk_mov_b32 v[6:7], v[0:1], v[0:1]
	v_pk_mov_b32 v[16:17], v[0:1], v[0:1]
	v_pk_mov_b32 v[18:19], v[0:1], v[0:1]
	v_pk_mov_b32 v[20:21], v[0:1], v[0:1]
	v_pk_mov_b32 v[22:23], v[0:1], v[0:1]
	v_pk_mov_b32 v[32:33], v[0:1], v[0:1]
	v_pk_mov_b32 v[34:35], v[0:1], v[0:1]
	v_pk_mov_b32 v[36:37], v[0:1], v[0:1]
	v_pk_mov_b32 v[38:39], v[0:1], v[0:1]
	v_pk_mov_b32 v[48:49], v[0:1], v[0:1]
	v_pk_mov_b32 v[50:51], v[0:1], v[0:1]
	v_pk_mov_b32 v[52:53], v[0:1], v[0:1]
	v_pk_mov_b32 v[54:55], v[0:1], v[0:1]
	v_pk_mov_b32 v[8:9], v[0:1], v[0:1]
	v_pk_mov_b32 v[10:11], v[0:1], v[0:1]
	v_pk_mov_b32 v[12:13], v[0:1], v[0:1]
	v_pk_mov_b32 v[14:15], v[0:1], v[0:1]
	v_pk_mov_b32 v[24:25], v[0:1], v[0:1]
	v_pk_mov_b32 v[26:27], v[0:1], v[0:1]
	v_pk_mov_b32 v[28:29], v[0:1], v[0:1]
	v_pk_mov_b32 v[30:31], v[0:1], v[0:1]
	v_pk_mov_b32 v[40:41], v[0:1], v[0:1]
	v_pk_mov_b32 v[42:43], v[0:1], v[0:1]
	v_pk_mov_b32 v[44:45], v[0:1], v[0:1]
	v_pk_mov_b32 v[46:47], v[0:1], v[0:1]
	v_pk_mov_b32 v[56:57], v[0:1], v[0:1]
	v_pk_mov_b32 v[58:59], v[0:1], v[0:1]
	v_pk_mov_b32 v[60:61], v[0:1], v[0:1]
	v_pk_mov_b32 v[62:63], v[0:1], v[0:1]
	v_pk_mov_b32 v[64:65], v[0:1], v[0:1]
	v_pk_mov_b32 v[66:67], v[0:1], v[0:1]
	v_pk_mov_b32 v[68:69], v[0:1], v[0:1]
	v_pk_mov_b32 v[70:71], v[0:1], v[0:1]
	v_pk_mov_b32 v[80:81], v[0:1], v[0:1]
	v_pk_mov_b32 v[82:83], v[0:1], v[0:1]
	v_pk_mov_b32 v[84:85], v[0:1], v[0:1]
	v_pk_mov_b32 v[86:87], v[0:1], v[0:1]
	v_pk_mov_b32 v[96:97], v[0:1], v[0:1]
	v_pk_mov_b32 v[98:99], v[0:1], v[0:1]
	v_pk_mov_b32 v[100:101], v[0:1], v[0:1]
	v_pk_mov_b32 v[102:103], v[0:1], v[0:1]
	v_pk_mov_b32 v[112:113], v[0:1], v[0:1]
	v_pk_mov_b32 v[114:115], v[0:1], v[0:1]
	v_pk_mov_b32 v[116:117], v[0:1], v[0:1]
	v_pk_mov_b32 v[118:119], v[0:1], v[0:1]
	v_pk_mov_b32 v[72:73], v[0:1], v[0:1]
	v_pk_mov_b32 v[74:75], v[0:1], v[0:1]
	v_pk_mov_b32 v[76:77], v[0:1], v[0:1]
	v_pk_mov_b32 v[78:79], v[0:1], v[0:1]
	v_pk_mov_b32 v[88:89], v[0:1], v[0:1]
	v_pk_mov_b32 v[90:91], v[0:1], v[0:1]
	v_pk_mov_b32 v[92:93], v[0:1], v[0:1]
	v_pk_mov_b32 v[94:95], v[0:1], v[0:1]
	v_pk_mov_b32 v[104:105], v[0:1], v[0:1]
	v_pk_mov_b32 v[106:107], v[0:1], v[0:1]
	v_pk_mov_b32 v[108:109], v[0:1], v[0:1]
	v_pk_mov_b32 v[110:111], v[0:1], v[0:1]
	v_pk_mov_b32 v[120:121], v[0:1], v[0:1]
	v_pk_mov_b32 v[122:123], v[0:1], v[0:1]
	v_pk_mov_b32 v[124:125], v[0:1], v[0:1]
	v_pk_mov_b32 v[126:127], v[0:1], v[0:1]

; template <class Epi, class Sched, bool ALIGN_EPI = false, bool SP2 = false>
; __device__ __forceinline__ void gemm_phase(PG8_LAS unsigned char* lds, const Gemm g, const Sched& S, const Epi& E, int tid_in) {
;     ...
;         const char* nA = has_next ? (const char*)g.A + (size_t)nxt.pm * tstep : cA; const char* nB = has_next ? (const char*)g.Bt + (size_t)nxt.pn * tstep : cB;
;         for (int t = 0; t < nt; t += 2) {
;             const bool last = (t == nt - 2);
;             const char* a1 = cA + (size_t)(t + 1) * kstep;
;             const char* a2 = last ? nA : cA + (size_t)(t + 2) * kstep; const char* b2 = last ? nB : cB + (size_t)(t + 2) * kstep;
;             const char* a3 = a2 + kstep; const char* b3 = b2 + kstep;
;             if (last && has_next) S.a_ready(nxt);
;             if constexpr (SP2) {
;             PG8_LDB(B0, 0, 0); PG8_LDB(B1, 0, 1); PG8_SCHED; PG8_LDA(At, 0, 0); PG8_STAGE(PG8_SA(1, 1), a1 + hstep, voffA);
;             PG8_WAIT_V(8); PG8_WAIT_L(0); PG8_BAR; PG8_MMA(0, 0, At, B0); PG8_MMA(0, 1, At, B1); PG8_BAR; PG8_SCHED;
;             PG8_LDA(At, 0, 1); PG8_STAGE(PG8_SB(0, 0), b2, voffB); PG8_STAGE(PG8_SB(0, 1), b2 + hstep, voffB); PG8_STAGE(PG8_SA(0, 0), a2, voffA);
;             PG8_WAIT_V(8); PG8_WAIT_L(0); PG8_BAR; PG8_MMA(1, 0, At, B0); PG8_MMA(1, 1, At, B1); PG8_BAR; PG8_SCHED;
;             PG8_LDB(B0, 1, 0); PG8_LDB(B1, 1, 1); PG8_SCHED; PG8_LDA(At, 1, 0); PG8_STAGE(PG8_SA(0, 1), a2 + hstep, voffA);
;             PG8_WAIT_V(8); PG8_WAIT_L(0); PG8_BAR; PG8_MMA(0, 0, At, B0); PG8_MMA(0, 1, At, B1); PG8_BAR; PG8_SCHED;
;             PG8_LDA(At, 1, 1); PG8_STAGE(PG8_SB(1, 0), b3, voffB); PG8_STAGE(PG8_SB(1, 1), b3 + hstep, voffB); PG8_STAGE(PG8_SA(1, 0), a3, voffA);
;             PG8_WAIT_V(8); PG8_WAIT_L(0); PG8_BAR; PG8_MMA(1, 0, At, B0); PG8_MMA(1, 1, At, B1); PG8_BAR; PG8_SCHED;
;             } else {
;             PG8_LDB(B0, 0, 0); PG8_SCHED; PG8_LDA(At, 0, 0); PG8_STAGE(PG8_SA(1, 1), a1 + hstep, voffA);
;             PG8_WAIT_L(8); PG8_BAR; PG8_WAIT_L(0); PG8_MMA(0, 0, At, B0); PG8_BAR; PG8_SCHED;
;             PG8_LDB(B1, 0, 1); PG8_STAGE(PG8_SB(0, 0), b2, voffB);
;             PG8_BAR; PG8_WAIT_L(0); PG8_MMA(0, 1, At, B1); PG8_BAR;
;             PG8_LDA(At, 0, 1); PG8_STAGE(PG8_SA(0, 0), a2, voffA);
;             PG8_BAR; PG8_WAIT_L(0); PG8_MMA(1, 0, At, B0); PG8_BAR; PG8_SCHED;
.LBB0_711:
	s_ashr_i32 s37, s36, 31
	s_lshl_b64 s[12:13], s[36:37], 19
	s_add_u32 s38, s4, s12
	s_addc_u32 s39, s5, s13
	s_and_b64 s[12:13], s[10:11], exec
	s_cselect_b32 s37, s39, s51
	s_cselect_b32 s65, s38, s50
	s_ashr_i32 s35, s34, 31
	s_lshl_b64 s[12:13], s[34:35], 19
	s_add_u32 s40, s1, s12
	s_addc_u32 s41, s3, s13
	s_and_b64 s[12:13], s[10:11], exec
	s_cselect_b32 s35, s41, s49
	s_cselect_b32 s66, s40, s48
	s_add_u32 s67, s48, 0x100
	s_addc_u32 s68, s49, 0
	s_add_u32 s12, s50, 0x40080
	v_mov_b32_e32 v0, 0
	v_mov_b32_e32 v1, v0
	s_addc_u32 s13, s51, 0
	s_mov_b32 s69, -2
	v_pk_mov_b32 v[2:3], v[0:1], v[0:1]
	v_pk_mov_b32 v[4:5], v[0:1], v[0:1]
	v_pk_mov_b32 v[6:7], v[0:1], v[0:1]
	v_pk_mov_b32 v[16:17], v[0:1], v[0:1]
	v_pk_mov_b32 v[18:19], v[0:1], v[0:1]
	v_pk_mov_b32 v[20:21], v[0:1], v[0:1]
	v_pk_mov_b32 v[22:23], v[0:1], v[0:1]
	v_pk_mov_b32 v[32:33], v[0:1], v[0:1]
	v_pk_mov_b32 v[34:35], v[0:1], v[0:1]
	v_pk_mov_b32 v[36:37], v[0:1], v[0:1]
	v_pk_mov_b32 v[38:39], v[0:1], v[0:1]
	v_pk_mov_b32 v[48:49], v[0:1], v[0:1]
	v_pk_mov_b32 v[50:51], v[0:1], v[0:1]
	v_pk_mov_b32 v[52:53], v[0:1], v[0:1]
	v_pk_mov_b32 v[54:55], v[0:1], v[0:1]
	v_pk_mov_b32 v[8:9], v[0:1], v[0:1]
	v_pk_mov_b32 v[10:11], v[0:1], v[0:1]
	v_pk_mov_b32 v[12:13], v[0:1], v[0:1]
	v_pk_mov_b32 v[14:15], v[0:1], v[0:1]
	v_pk_mov_b32 v[24:25], v[0:1], v[0:1]
	v_pk_mov_b32 v[26:27], v[0:1], v[0:1]
	v_pk_mov_b32 v[28:29], v[0:1], v[0:1]
	v_pk_mov_b32 v[30:31], v[0:1], v[0:1]
	v_pk_mov_b32 v[40:41], v[0:1], v[0:1]
	v_pk_mov_b32 v[42:43], v[0:1], v[0:1]
	v_pk_mov_b32 v[44:45], v[0:1], v[0:1]
	v_pk_mov_b32 v[46:47], v[0:1], v[0:1]
	v_pk_mov_b32 v[56:57], v[0:1], v[0:1]
	v_pk_mov_b32 v[58:59], v[0:1], v[0:1]
	v_pk_mov_b32 v[60:61], v[0:1], v[0:1]
	v_pk_mov_b32 v[62:63], v[0:1], v[0:1]
	v_pk_mov_b32 v[64:65], v[0:1], v[0:1]
	v_pk_mov_b32 v[66:67], v[0:1], v[0:1]
	v_pk_mov_b32 v[68:69], v[0:1], v[0:1]
	v_pk_mov_b32 v[70:71], v[0:1], v[0:1]
	v_pk_mov_b32 v[80:81], v[0:1], v[0:1]
	v_pk_mov_b32 v[82:83], v[0:1], v[0:1]
	v_pk_mov_b32 v[84:85], v[0:1], v[0:1]
	v_pk_mov_b32 v[86:87], v[0:1], v[0:1]
	v_pk_mov_b32 v[96:97], v[0:1], v[0:1]
	v_pk_mov_b32 v[98:99], v[0:1], v[0:1]
	v_pk_mov_b32 v[100:101], v[0:1], v[0:1]
	v_pk_mov_b32 v[102:103], v[0:1], v[0:1]
	v_pk_mov_b32 v[112:113], v[0:1], v[0:1]
	v_pk_mov_b32 v[114:115], v[0:1], v[0:1]
	v_pk_mov_b32 v[116:117], v[0:1], v[0:1]
	v_pk_mov_b32 v[118:119], v[0:1], v[0:1]
	v_pk_mov_b32 v[72:73], v[0:1], v[0:1]
	v_pk_mov_b32 v[74:75], v[0:1], v[0:1]
	v_pk_mov_b32 v[76:77], v[0:1], v[0:1]
	v_pk_mov_b32 v[78:79], v[0:1], v[0:1]
	v_pk_mov_b32 v[88:89], v[0:1], v[0:1]
	v_pk_mov_b32 v[90:91], v[0:1], v[0:1]
	v_pk_mov_b32 v[92:93], v[0:1], v[0:1]
	v_pk_mov_b32 v[94:95], v[0:1], v[0:1]
	v_pk_mov_b32 v[104:105], v[0:1], v[0:1]
	v_pk_mov_b32 v[106:107], v[0:1], v[0:1]
	v_pk_mov_b32 v[108:109], v[0:1], v[0:1]
	v_pk_mov_b32 v[110:111], v[0:1], v[0:1]
	v_pk_mov_b32 v[120:121], v[0:1], v[0:1]
	v_pk_mov_b32 v[122:123], v[0:1], v[0:1]
	v_pk_mov_b32 v[124:125], v[0:1], v[0:1]
	v_pk_mov_b32 v[126:127], v[0:1], v[0:1]
	v_readlane_b32 s98, v252, 5
	s_nop 1
	s_lshl_b32 s98, s98, 5
	s_add_i32 m0, s98, 0x20080
	s_lshl_b32 s98, s46, 14
	s_add_u32 s98, s100, s98
	s_addc_u32 s99, s101, 0
	global_load_lds_dwordx4 v238, s[98:99]
	global_load_lds_dwordx4 v238, s[98:99] offset:1024

; template <class Epi, class Sched, bool ALIGN_EPI = false, bool SP2 = false>
; __device__ __forceinline__ void gemm_phase(PG8_LAS unsigned char* lds, const Gemm g, const Sched& S, const Epi& E, int tid_in) {
;     ...
;         const char* nA = has_next ? (const char*)g.A + (size_t)nxt.pm * tstep : cA; const char* nB = has_next ? (const char*)g.Bt + (size_t)nxt.pn * tstep : cB;
;         for (int t = 0; t < nt; t += 2) {
;             const bool last = (t == nt - 2);
;             const char* a1 = cA + (size_t)(t + 1) * kstep;
;             const char* a2 = last ? nA : cA + (size_t)(t + 2) * kstep; const char* b2 = last ? nB : cB + (size_t)(t + 2) * kstep;
;             const char* a3 = a2 + kstep; const char* b3 = b2 + kstep;
;             if (last && has_next) S.a_ready(nxt);
;             if constexpr (SP2) {
;             PG8_LDB(B0, 0, 0); PG8_LDB(B1, 0, 1); PG8_SCHED; PG8_LDA(At, 0, 0); PG8_STAGE(PG8_SA(1, 1), a1 + hstep, voffA);
;             PG8_WAIT_V(8); PG8_WAIT_L(0); PG8_BAR; PG8_MMA(0, 0, At, B0); PG8_MMA(0, 1, At, B1); PG8_BAR; PG8_SCHED;
;             PG8_LDA(At, 0, 1); PG8_STAGE(PG8_SB(0, 0), b2, voffB); PG8_STAGE(PG8_SB(0, 1), b2 + hstep, voffB); PG8_STAGE(PG8_SA(0, 0), a2, voffA);
;             PG8_WAIT_V(8); PG8_WAIT_L(0); PG8_BAR; PG8_MMA(1, 0, At, B0); PG8_MMA(1, 1, At, B1); PG8_BAR; PG8_SCHED;
;             PG8_LDB(B0, 1, 0); PG8_LDB(B1, 1, 1); PG8_SCHED; PG8_LDA(At, 1, 0); PG8_STAGE(PG8_SA(0, 1), a2 + hstep, voffA);
;             PG8_WAIT_V(8); PG8_WAIT_L(0); PG8_BAR; PG8_MMA(0, 0, At, B0); PG8_MMA(0, 1, At, B1); PG8_BAR; PG8_SCHED;
;             PG8_LDA(At, 1, 1); PG8_STAGE(PG8_SB(1, 0), b3, voffB); PG8_STAGE(PG8_SB(1, 1), b3 + hstep, voffB); PG8_STAGE(PG8_SA(1, 0), a3, voffA);
;             PG8_WAIT_V(8); PG8_WAIT_L(0); PG8_BAR; PG8_MMA(1, 0, At, B0); PG8_MMA(1, 1, At, B1); PG8_BAR; PG8_SCHED;
;             } else {
;             PG8_LDB(B0, 0, 0); PG8_SCHED; PG8_LDA(At, 0, 0); PG8_STAGE(PG8_SA(1, 1), a1 + hstep, voffA);
;             PG8_WAIT_L(8); PG8_BAR; PG8_WAIT_L(0); PG8_MMA(0, 0, At, B0); PG8_BAR; PG8_SCHED;
;             PG8_LDB(B1, 0, 1); PG8_STAGE(PG8_SB(0, 0), b2, voffB);
;             PG8_BAR; PG8_WAIT_L(0); PG8_MMA(0, 1, At, B1); PG8_BAR;
;             PG8_LDA(At, 0, 1); PG8_STAGE(PG8_SA(0, 0), a2, voffA);
;             PG8_BAR; PG8_WAIT_L(0); PG8_MMA(1, 0, At, B0); PG8_BAR; PG8_SCHED;
.LBB0_911:
	s_ashr_i32 s49, s48, 31
	s_lshl_b64 s[14:15], s[48:49], 19
	s_add_u32 s50, s0, s14
	s_addc_u32 s51, s3, s15
	s_and_b64 s[14:15], s[16:17], exec
	s_cselect_b32 s49, s51, s59
	s_cselect_b32 s55, s50, s58
	s_ashr_i32 s47, s46, 31
	s_lshl_b64 s[14:15], s[46:47], 19
	s_add_u32 s52, s33, s14
	s_addc_u32 s53, s40, s15
	s_and_b64 s[14:15], s[16:17], exec
	s_cselect_b32 s47, s53, s57
	s_cselect_b32 s76, s52, s56
	s_add_u32 s80, s56, 0x100
	s_addc_u32 s81, s57, 0
	s_add_u32 s56, s58, 0x40080
	v_mov_b32_e32 v0, 0
	v_mov_b32_e32 v1, v0
	s_addc_u32 s57, s59, 0
	s_mov_b32 vcc_lo, -2
	s_waitcnt lgkmcnt(0)
	v_pk_mov_b32 v[2:3], v[0:1], v[0:1]
	v_pk_mov_b32 v[4:5], v[0:1], v[0:1]
	v_pk_mov_b32 v[6:7], v[0:1], v[0:1]
	v_pk_mov_b32 v[16:17], v[0:1], v[0:1]
	v_pk_mov_b32 v[18:19], v[0:1], v[0:1]
	v_pk_mov_b32 v[20:21], v[0:1], v[0:1]
	v_pk_mov_b32 v[22:23], v[0:1], v[0:1]
	v_pk_mov_b32 v[32:33], v[0:1], v[0:1]
	v_pk_mov_b32 v[34:35], v[0:1], v[0:1]
	v_pk_mov_b32 v[36:37], v[0:1], v[0:1]
	v_pk_mov_b32 v[38:39], v[0:1], v[0:1]
	v_pk_mov_b32 v[48:49], v[0:1], v[0:1]
	v_pk_mov_b32 v[50:51], v[0:1], v[0:1]
	v_pk_mov_b32 v[52:53], v[0:1], v[0:1]
	v_pk_mov_b32 v[54:55], v[0:1], v[0:1]
	v_pk_mov_b32 v[8:9], v[0:1], v[0:1]
	v_pk_mov_b32 v[10:11], v[0:1], v[0:1]
	v_pk_mov_b32 v[12:13], v[0:1], v[0:1]
	v_pk_mov_b32 v[14:15], v[0:1], v[0:1]
	v_pk_mov_b32 v[24:25], v[0:1], v[0:1]
	v_pk_mov_b32 v[26:27], v[0:1], v[0:1]
	v_pk_mov_b32 v[28:29], v[0:1], v[0:1]
	v_pk_mov_b32 v[30:31], v[0:1], v[0:1]
	v_pk_mov_b32 v[40:41], v[0:1], v[0:1]
	v_pk_mov_b32 v[42:43], v[0:1], v[0:1]
	v_pk_mov_b32 v[44:45], v[0:1], v[0:1]
	v_pk_mov_b32 v[46:47], v[0:1], v[0:1]
	v_pk_mov_b32 v[56:57], v[0:1], v[0:1]
	v_pk_mov_b32 v[58:59], v[0:1], v[0:1]
	v_pk_mov_b32 v[60:61], v[0:1], v[0:1]
	v_pk_mov_b32 v[62:63], v[0:1], v[0:1]
	v_pk_mov_b32 v[64:65], v[0:1], v[0:1]
	v_pk_mov_b32 v[66:67], v[0:1], v[0:1]
	v_pk_mov_b32 v[68:69], v[0:1], v[0:1]
	v_pk_mov_b32 v[70:71], v[0:1], v[0:1]
	v_pk_mov_b32 v[80:81], v[0:1], v[0:1]
	v_pk_mov_b32 v[82:83], v[0:1], v[0:1]
	v_pk_mov_b32 v[84:85], v[0:1], v[0:1]
	v_pk_mov_b32 v[86:87], v[0:1], v[0:1]
	v_pk_mov_b32 v[96:97], v[0:1], v[0:1]
	v_pk_mov_b32 v[98:99], v[0:1], v[0:1]
	v_pk_mov_b32 v[100:101], v[0:1], v[0:1]
	v_pk_mov_b32 v[102:103], v[0:1], v[0:1]
	v_pk_mov_b32 v[112:113], v[0:1], v[0:1]
	v_pk_mov_b32 v[114:115], v[0:1], v[0:1]
	v_pk_mov_b32 v[116:117], v[0:1], v[0:1]
	v_pk_mov_b32 v[118:119], v[0:1], v[0:1]
	v_pk_mov_b32 v[72:73], v[0:1], v[0:1]
	v_pk_mov_b32 v[74:75], v[0:1], v[0:1]
	v_pk_mov_b32 v[76:77], v[0:1], v[0:1]
	v_pk_mov_b32 v[78:79], v[0:1], v[0:1]
	v_pk_mov_b32 v[88:89], v[0:1], v[0:1]
	v_pk_mov_b32 v[90:91], v[0:1], v[0:1]
	v_pk_mov_b32 v[92:93], v[0:1], v[0:1]
	v_pk_mov_b32 v[94:95], v[0:1], v[0:1]
	v_pk_mov_b32 v[104:105], v[0:1], v[0:1]
	v_pk_mov_b32 v[106:107], v[0:1], v[0:1]
	v_pk_mov_b32 v[108:109], v[0:1], v[0:1]
	v_pk_mov_b32 v[110:111], v[0:1], v[0:1]
	v_pk_mov_b32 v[124:125], v[0:1], v[0:1]
	v_pk_mov_b32 v[126:127], v[0:1], v[0:1]
	v_pk_mov_b32 v[128:129], v[0:1], v[0:1]
	v_pk_mov_b32 v[130:131], v[0:1], v[0:1]

; template <class Epi, class Sched, bool ALIGN_EPI = false, bool SP2 = false>
; __device__ __forceinline__ void gemm_phase(PG8_LAS unsigned char* lds, const Gemm g, const Sched& S, const Epi& E, int tid_in) {
;     ...
;         const char* nA = has_next ? (const char*)g.A + (size_t)nxt.pm * tstep : cA; const char* nB = has_next ? (const char*)g.Bt + (size_t)nxt.pn * tstep : cB;
;         for (int t = 0; t < nt; t += 2) {
;             const bool last = (t == nt - 2);
;             const char* a1 = cA + (size_t)(t + 1) * kstep;
;             const char* a2 = last ? nA : cA + (size_t)(t + 2) * kstep; const char* b2 = last ? nB : cB + (size_t)(t + 2) * kstep;
;             const char* a3 = a2 + kstep; const char* b3 = b2 + kstep;
;             if (last && has_next) S.a_ready(nxt);
;             if constexpr (SP2) {
;             PG8_LDB(B0, 0, 0); PG8_LDB(B1, 0, 1); PG8_SCHED; PG8_LDA(At, 0, 0); PG8_STAGE(PG8_SA(1, 1), a1 + hstep, voffA);
;             PG8_WAIT_V(8); PG8_WAIT_L(0); PG8_BAR; PG8_MMA(0, 0, At, B0); PG8_MMA(0, 1, At, B1); PG8_BAR; PG8_SCHED;
;             PG8_LDA(At, 0, 1); PG8_STAGE(PG8_SB(0, 0), b2, voffB); PG8_STAGE(PG8_SB(0, 1), b2 + hstep, voffB); PG8_STAGE(PG8_SA(0, 0), a2, voffA);
;             PG8_WAIT_V(8); PG8_WAIT_L(0); PG8_BAR; PG8_MMA(1, 0, At, B0); PG8_MMA(1, 1, At, B1); PG8_BAR; PG8_SCHED;
;             PG8_LDB(B0, 1, 0); PG8_LDB(B1, 1, 1); PG8_SCHED; PG8_LDA(At, 1, 0); PG8_STAGE(PG8_SA(0, 1), a2 + hstep, voffA);
;             PG8_WAIT_V(8); PG8_WAIT_L(0); PG8_BAR; PG8_MMA(0, 0, At, B0); PG8_MMA(0, 1, At, B1); PG8_BAR; PG8_SCHED;
;             PG8_LDA(At, 1, 1); PG8_STAGE(PG8_SB(1, 0), b3, voffB); PG8_STAGE(PG8_SB(1, 1), b3 + hstep, voffB); PG8_STAGE(PG8_SA(1, 0), a3, voffA);
;             PG8_WAIT_V(8); PG8_WAIT_L(0); PG8_BAR; PG8_MMA(1, 0, At, B0); PG8_MMA(1, 1, At, B1); PG8_BAR; PG8_SCHED;
;             } else {
;             PG8_LDB(B0, 0, 0); PG8_SCHED; PG8_LDA(At, 0, 0); PG8_STAGE(PG8_SA(1, 1), a1 + hstep, voffA);
;             PG8_WAIT_L(8); PG8_BAR; PG8_WAIT_L(0); PG8_MMA(0, 0, At, B0); PG8_BAR; PG8_SCHED;
;             PG8_LDB(B1, 0, 1); PG8_STAGE(PG8_SB(0, 0), b2, voffB);
;             PG8_BAR; PG8_WAIT_L(0); PG8_MMA(0, 1, At, B1); PG8_BAR;
;             PG8_LDA(At, 0, 1); PG8_STAGE(PG8_SA(0, 0), a2, voffA);
;             PG8_BAR; PG8_WAIT_L(0); PG8_MMA(1, 0, At, B0); PG8_BAR; PG8_SCHED;
.LBB0_995:
	s_ashr_i32 s43, s42, 31
	s_lshl_b64 s[14:15], s[42:43], 19
	s_add_u32 s44, s0, s14
	s_addc_u32 s45, s3, s15
	s_and_b64 s[14:15], s[16:17], exec
	s_cselect_b32 s43, s45, s53
	s_cselect_b32 s69, s44, s52
	s_ashr_i32 s27, s26, 31
	s_lshl_b64 s[14:15], s[26:27], 19
	s_add_u32 s46, s12, s14
	s_addc_u32 s47, s13, s15
	s_and_b64 s[14:15], s[16:17], exec
	s_cselect_b32 s27, s47, s51
	s_cselect_b32 s70, s46, s50
	s_add_u32 s71, s50, 0x100
	s_addc_u32 s72, s51, 0
	s_add_u32 s50, s52, 0x40080
	v_mov_b32_e32 v0, 0
	v_mov_b32_e32 v1, v0
	s_addc_u32 s51, s53, 0
	s_mov_b32 s73, -2
	v_pk_mov_b32 v[2:3], v[0:1], v[0:1]
	v_pk_mov_b32 v[4:5], v[0:1], v[0:1]
	v_pk_mov_b32 v[6:7], v[0:1], v[0:1]
	v_pk_mov_b32 v[16:17], v[0:1], v[0:1]
	v_pk_mov_b32 v[18:19], v[0:1], v[0:1]
	v_pk_mov_b32 v[20:21], v[0:1], v[0:1]
	v_pk_mov_b32 v[22:23], v[0:1], v[0:1]
	v_pk_mov_b32 v[32:33], v[0:1], v[0:1]
	v_pk_mov_b32 v[34:35], v[0:1], v[0:1]
	v_pk_mov_b32 v[36:37], v[0:1], v[0:1]
	v_pk_mov_b32 v[38:39], v[0:1], v[0:1]
	v_pk_mov_b32 v[48:49], v[0:1], v[0:1]
	v_pk_mov_b32 v[50:51], v[0:1], v[0:1]
	v_pk_mov_b32 v[52:53], v[0:1], v[0:1]
	v_pk_mov_b32 v[54:55], v[0:1], v[0:1]
	v_pk_mov_b32 v[8:9], v[0:1], v[0:1]
	v_pk_mov_b32 v[10:11], v[0:1], v[0:1]
	v_pk_mov_b32 v[12:13], v[0:1], v[0:1]
	v_pk_mov_b32 v[14:15], v[0:1], v[0:1]
	v_pk_mov_b32 v[24:25], v[0:1], v[0:1]
	v_pk_mov_b32 v[26:27], v[0:1], v[0:1]
	v_pk_mov_b32 v[28:29], v[0:1], v[0:1]
	v_pk_mov_b32 v[30:31], v[0:1], v[0:1]
	v_pk_mov_b32 v[40:41], v[0:1], v[0:1]
	v_pk_mov_b32 v[42:43], v[0:1], v[0:1]
	v_pk_mov_b32 v[44:45], v[0:1], v[0:1]
	v_pk_mov_b32 v[46:47], v[0:1], v[0:1]
	v_pk_mov_b32 v[56:57], v[0:1], v[0:1]
	v_pk_mov_b32 v[58:59], v[0:1], v[0:1]
	v_pk_mov_b32 v[60:61], v[0:1], v[0:1]
	v_pk_mov_b32 v[62:63], v[0:1], v[0:1]
	v_pk_mov_b32 v[64:65], v[0:1], v[0:1]
	v_pk_mov_b32 v[66:67], v[0:1], v[0:1]
	v_pk_mov_b32 v[68:69], v[0:1], v[0:1]
	v_pk_mov_b32 v[70:71], v[0:1], v[0:1]
	v_pk_mov_b32 v[80:81], v[0:1], v[0:1]
	v_pk_mov_b32 v[82:83], v[0:1], v[0:1]
	v_pk_mov_b32 v[84:85], v[0:1], v[0:1]
	v_pk_mov_b32 v[86:87], v[0:1], v[0:1]
	v_pk_mov_b32 v[96:97], v[0:1], v[0:1]
	v_pk_mov_b32 v[98:99], v[0:1], v[0:1]
	v_pk_mov_b32 v[100:101], v[0:1], v[0:1]
	v_pk_mov_b32 v[102:103], v[0:1], v[0:1]
	v_pk_mov_b32 v[112:113], v[0:1], v[0:1]
	v_pk_mov_b32 v[114:115], v[0:1], v[0:1]
	v_pk_mov_b32 v[116:117], v[0:1], v[0:1]
	v_pk_mov_b32 v[118:119], v[0:1], v[0:1]
	v_pk_mov_b32 v[72:73], v[0:1], v[0:1]
	v_pk_mov_b32 v[74:75], v[0:1], v[0:1]
	v_pk_mov_b32 v[76:77], v[0:1], v[0:1]
	v_pk_mov_b32 v[78:79], v[0:1], v[0:1]
	v_pk_mov_b32 v[88:89], v[0:1], v[0:1]
	v_pk_mov_b32 v[90:91], v[0:1], v[0:1]
	v_pk_mov_b32 v[92:93], v[0:1], v[0:1]
	v_pk_mov_b32 v[94:95], v[0:1], v[0:1]
	v_pk_mov_b32 v[104:105], v[0:1], v[0:1]
	v_pk_mov_b32 v[106:107], v[0:1], v[0:1]
	v_pk_mov_b32 v[108:109], v[0:1], v[0:1]
	v_pk_mov_b32 v[110:111], v[0:1], v[0:1]
	v_pk_mov_b32 v[120:121], v[0:1], v[0:1]
	v_pk_mov_b32 v[122:123], v[0:1], v[0:1]
	v_pk_mov_b32 v[124:125], v[0:1], v[0:1]
	v_pk_mov_b32 v[126:127], v[0:1], v[0:1]
	v_readlane_b32 s98, v252, 5
	s_nop 1
	s_lshl_b32 s98, s98, 5
	s_add_i32 m0, s98, 0x20080
	s_lshl_b32 s98, s48, 14
	s_add_u32 s98, s100, s98
	s_addc_u32 s99, s101, 0
	global_load_lds_dwordx4 v238, s[98:99]
	global_load_lds_dwordx4 v238, s[98:99] offset:1024

; template <class Epi, class Sched, bool ALIGN_EPI = false, bool SP2 = false>
; __device__ __forceinline__ void gemm_phase(PG8_LAS unsigned char* lds, const Gemm g, const Sched& S, const Epi& E, int tid_in) {
;     ...
; #pragma unroll
;         for (int a = 0; a < 2; ++a)
; #pragma unroll
;             for (int b = 0; b < 2; ++b)
; #pragma unroll
;                 for (int m = 0; m < 4; ++m)
; #pragma unroll
;                     for (int n = 0; n < 2; ++n) acc[a][b][m][n] = (f32x4){0.f, 0.f, 0.f, 0.f};
;         cur = nxt; cA = nA; cB = nB; ++ui;
.LBB0_1077:
	s_add_u32 s73, s52, 0x100
	v_mov_b32_e32 v0, 0
	v_mov_b32_e32 v1, v0
	s_addc_u32 s76, s53, 0
	s_mov_b32 s78, -2
	s_waitcnt lgkmcnt(0)
	v_pk_mov_b32 v[2:3], v[0:1], v[0:1]
	v_pk_mov_b32 v[4:5], v[0:1], v[0:1]
	v_pk_mov_b32 v[6:7], v[0:1], v[0:1]
	v_pk_mov_b32 v[16:17], v[0:1], v[0:1]
	v_pk_mov_b32 v[18:19], v[0:1], v[0:1]
	v_pk_mov_b32 v[20:21], v[0:1], v[0:1]
	v_pk_mov_b32 v[22:23], v[0:1], v[0:1]
	v_pk_mov_b32 v[32:33], v[0:1], v[0:1]
	v_pk_mov_b32 v[34:35], v[0:1], v[0:1]
	v_pk_mov_b32 v[36:37], v[0:1], v[0:1]
	v_pk_mov_b32 v[38:39], v[0:1], v[0:1]
	v_pk_mov_b32 v[48:49], v[0:1], v[0:1]
	v_pk_mov_b32 v[50:51], v[0:1], v[0:1]
	v_pk_mov_b32 v[52:53], v[0:1], v[0:1]
	v_pk_mov_b32 v[54:55], v[0:1], v[0:1]
	v_pk_mov_b32 v[8:9], v[0:1], v[0:1]
	v_pk_mov_b32 v[10:11], v[0:1], v[0:1]
	v_pk_mov_b32 v[12:13], v[0:1], v[0:1]
	v_pk_mov_b32 v[14:15], v[0:1], v[0:1]
	v_pk_mov_b32 v[24:25], v[0:1], v[0:1]
	v_pk_mov_b32 v[26:27], v[0:1], v[0:1]
	v_pk_mov_b32 v[28:29], v[0:1], v[0:1]
	v_pk_mov_b32 v[30:31], v[0:1], v[0:1]
	v_pk_mov_b32 v[40:41], v[0:1], v[0:1]
	v_pk_mov_b32 v[42:43], v[0:1], v[0:1]
	v_pk_mov_b32 v[44:45], v[0:1], v[0:1]
	v_pk_mov_b32 v[46:47], v[0:1], v[0:1]
	v_pk_mov_b32 v[56:57], v[0:1], v[0:1]
	v_pk_mov_b32 v[58:59], v[0:1], v[0:1]
	v_pk_mov_b32 v[60:61], v[0:1], v[0:1]
	v_pk_mov_b32 v[62:63], v[0:1], v[0:1]
	v_pk_mov_b32 v[64:65], v[0:1], v[0:1]
	v_pk_mov_b32 v[66:67], v[0:1], v[0:1]
	v_pk_mov_b32 v[68:69], v[0:1], v[0:1]
	v_pk_mov_b32 v[70:71], v[0:1], v[0:1]
	v_pk_mov_b32 v[80:81], v[0:1], v[0:1]
	v_pk_mov_b32 v[82:83], v[0:1], v[0:1]
	v_pk_mov_b32 v[84:85], v[0:1], v[0:1]
	v_pk_mov_b32 v[86:87], v[0:1], v[0:1]
	v_pk_mov_b32 v[96:97], v[0:1], v[0:1]
	v_pk_mov_b32 v[98:99], v[0:1], v[0:1]
	v_pk_mov_b32 v[100:101], v[0:1], v[0:1]
	v_pk_mov_b32 v[102:103], v[0:1], v[0:1]
	v_pk_mov_b32 v[112:113], v[0:1], v[0:1]
	v_pk_mov_b32 v[114:115], v[0:1], v[0:1]
	v_pk_mov_b32 v[116:117], v[0:1], v[0:1]
	v_pk_mov_b32 v[118:119], v[0:1], v[0:1]
	v_pk_mov_b32 v[72:73], v[0:1], v[0:1]
	v_pk_mov_b32 v[74:75], v[0:1], v[0:1]
	v_pk_mov_b32 v[76:77], v[0:1], v[0:1]
	v_pk_mov_b32 v[78:79], v[0:1], v[0:1]
	v_pk_mov_b32 v[88:89], v[0:1], v[0:1]
	v_pk_mov_b32 v[90:91], v[0:1], v[0:1]
	v_pk_mov_b32 v[92:93], v[0:1], v[0:1]
	v_pk_mov_b32 v[94:95], v[0:1], v[0:1]
	v_pk_mov_b32 v[104:105], v[0:1], v[0:1]
	v_pk_mov_b32 v[106:107], v[0:1], v[0:1]
	v_pk_mov_b32 v[108:109], v[0:1], v[0:1]
	v_pk_mov_b32 v[110:111], v[0:1], v[0:1]
	v_pk_mov_b32 v[124:125], v[0:1], v[0:1]
	v_pk_mov_b32 v[126:127], v[0:1], v[0:1]
	v_pk_mov_b32 v[128:129], v[0:1], v[0:1]
	v_pk_mov_b32 v[130:131], v[0:1], v[0:1]

; template <class Epi, class Sched, bool ALIGN_EPI = false, bool SP2 = false>
; __device__ __forceinline__ void gemm_phase(PG8_LAS unsigned char* lds, const Gemm g, const Sched& S, const Epi& E, int tid_in) {
;     ...
;         const char* nA = has_next ? (const char*)g.A + (size_t)nxt.pm * tstep : cA; const char* nB = has_next ? (const char*)g.Bt + (size_t)nxt.pn * tstep : cB;
;         for (int t = 0; t < nt; t += 2) {
;             const bool last = (t == nt - 2);
;             const char* a1 = cA + (size_t)(t + 1) * kstep;
;             const char* a2 = last ? nA : cA + (size_t)(t + 2) * kstep; const char* b2 = last ? nB : cB + (size_t)(t + 2) * kstep;
;             const char* a3 = a2 + kstep; const char* b3 = b2 + kstep;
;             if (last && has_next) S.a_ready(nxt);
;             if constexpr (SP2) {
;             PG8_LDB(B0, 0, 0); PG8_LDB(B1, 0, 1); PG8_SCHED; PG8_LDA(At, 0, 0); PG8_STAGE(PG8_SA(1, 1), a1 + hstep, voffA);
;             PG8_WAIT_V(8); PG8_WAIT_L(0); PG8_BAR; PG8_MMA(0, 0, At, B0); PG8_MMA(0, 1, At, B1); PG8_BAR; PG8_SCHED;
;             PG8_LDA(At, 0, 1); PG8_STAGE(PG8_SB(0, 0), b2, voffB); PG8_STAGE(PG8_SB(0, 1), b2 + hstep, voffB); PG8_STAGE(PG8_SA(0, 0), a2, voffA);
;             PG8_WAIT_V(8); PG8_WAIT_L(0); PG8_BAR; PG8_MMA(1, 0, At, B0); PG8_MMA(1, 1, At, B1); PG8_BAR; PG8_SCHED;
;             PG8_LDB(B0, 1, 0); PG8_LDB(B1, 1, 1); PG8_SCHED; PG8_LDA(At, 1, 0); PG8_STAGE(PG8_SA(0, 1), a2 + hstep, voffA);
;             PG8_WAIT_V(8); PG8_WAIT_L(0); PG8_BAR; PG8_MMA(0, 0, At, B0); PG8_MMA(0, 1, At, B1); PG8_BAR; PG8_SCHED;
;             PG8_LDA(At, 1, 1); PG8_STAGE(PG8_SB(1, 0), b3, voffB); PG8_STAGE(PG8_SB(1, 1), b3 + hstep, voffB); PG8_STAGE(PG8_SA(1, 0), a3, voffA);
;             PG8_WAIT_V(8); PG8_WAIT_L(0); PG8_BAR; PG8_MMA(1, 0, At, B0); PG8_MMA(1, 1, At, B1); PG8_BAR; PG8_SCHED;
;             } else {
;             PG8_LDB(B0, 0, 0); PG8_SCHED; PG8_LDA(At, 0, 0); PG8_STAGE(PG8_SA(1, 1), a1 + hstep, voffA);
;             PG8_WAIT_L(8); PG8_BAR; PG8_WAIT_L(0); PG8_MMA(0, 0, At, B0); PG8_BAR; PG8_SCHED;
;             PG8_LDB(B1, 0, 1); PG8_STAGE(PG8_SB(0, 0), b2, voffB);
;             PG8_BAR; PG8_WAIT_L(0); PG8_MMA(0, 1, At, B1); PG8_BAR;
;             PG8_LDA(At, 0, 1); PG8_STAGE(PG8_SA(0, 0), a2, voffA);
;             PG8_BAR; PG8_WAIT_L(0); PG8_MMA(1, 0, At, B0); PG8_BAR; PG8_SCHED;
.LBB0_1187:
	s_ashr_i32 s27, s26, 31
	s_lshl_b64 s[42:43], s[26:27], 19
	s_add_u32 s42, s59, s42
	s_addc_u32 s43, s60, s43
	s_and_b64 s[44:45], s[14:15], exec
	s_cselect_b32 s0, s43, s49
	s_cselect_b32 s13, s42, s48
	s_ashr_i32 s25, s24, 31
	s_lshl_b64 s[44:45], s[24:25], 19
	s_add_u32 s44, s3, s44
	s_addc_u32 s45, s58, s45
	s_and_b64 s[54:55], s[14:15], exec
	s_cselect_b32 s25, s45, s47
	s_cselect_b32 s27, s44, s46
	s_add_u32 s33, s46, 0x100
	s_addc_u32 s51, s47, 0
	s_add_u32 s46, s48, 0x40080
	v_mov_b32_e32 v0, 0
	v_mov_b32_e32 v1, v0
	s_addc_u32 s47, s49, 0
	s_mov_b32 s53, -2
	v_pk_mov_b32 v[2:3], v[0:1], v[0:1]
	v_pk_mov_b32 v[4:5], v[0:1], v[0:1]
	v_pk_mov_b32 v[6:7], v[0:1], v[0:1]
	v_pk_mov_b32 v[16:17], v[0:1], v[0:1]
	v_pk_mov_b32 v[18:19], v[0:1], v[0:1]
	v_pk_mov_b32 v[20:21], v[0:1], v[0:1]
	v_pk_mov_b32 v[22:23], v[0:1], v[0:1]
	v_pk_mov_b32 v[32:33], v[0:1], v[0:1]
	v_pk_mov_b32 v[34:35], v[0:1], v[0:1]
	v_pk_mov_b32 v[36:37], v[0:1], v[0:1]
	v_pk_mov_b32 v[38:39], v[0:1], v[0:1]
	v_pk_mov_b32 v[48:49], v[0:1], v[0:1]
	v_pk_mov_b32 v[50:51], v[0:1], v[0:1]
	v_pk_mov_b32 v[52:53], v[0:1], v[0:1]
	v_pk_mov_b32 v[54:55], v[0:1], v[0:1]
	v_pk_mov_b32 v[8:9], v[0:1], v[0:1]
	v_pk_mov_b32 v[10:11], v[0:1], v[0:1]
	v_pk_mov_b32 v[12:13], v[0:1], v[0:1]
	v_pk_mov_b32 v[14:15], v[0:1], v[0:1]
	v_pk_mov_b32 v[24:25], v[0:1], v[0:1]
	v_pk_mov_b32 v[26:27], v[0:1], v[0:1]
	v_pk_mov_b32 v[28:29], v[0:1], v[0:1]
	v_pk_mov_b32 v[30:31], v[0:1], v[0:1]
	v_pk_mov_b32 v[40:41], v[0:1], v[0:1]
	v_pk_mov_b32 v[42:43], v[0:1], v[0:1]
	v_pk_mov_b32 v[44:45], v[0:1], v[0:1]
	v_pk_mov_b32 v[46:47], v[0:1], v[0:1]
	v_pk_mov_b32 v[56:57], v[0:1], v[0:1]
	v_pk_mov_b32 v[58:59], v[0:1], v[0:1]
	v_pk_mov_b32 v[60:61], v[0:1], v[0:1]
	v_pk_mov_b32 v[62:63], v[0:1], v[0:1]
	v_pk_mov_b32 v[64:65], v[0:1], v[0:1]
	v_pk_mov_b32 v[66:67], v[0:1], v[0:1]
	v_pk_mov_b32 v[68:69], v[0:1], v[0:1]
	v_pk_mov_b32 v[70:71], v[0:1], v[0:1]
	v_pk_mov_b32 v[80:81], v[0:1], v[0:1]
	v_pk_mov_b32 v[82:83], v[0:1], v[0:1]
	v_pk_mov_b32 v[84:85], v[0:1], v[0:1]
	v_pk_mov_b32 v[86:87], v[0:1], v[0:1]
	v_pk_mov_b32 v[96:97], v[0:1], v[0:1]
	v_pk_mov_b32 v[98:99], v[0:1], v[0:1]
	v_pk_mov_b32 v[100:101], v[0:1], v[0:1]
	v_pk_mov_b32 v[102:103], v[0:1], v[0:1]
	v_pk_mov_b32 v[112:113], v[0:1], v[0:1]
	v_pk_mov_b32 v[114:115], v[0:1], v[0:1]
	v_pk_mov_b32 v[116:117], v[0:1], v[0:1]
	v_pk_mov_b32 v[118:119], v[0:1], v[0:1]
	v_pk_mov_b32 v[72:73], v[0:1], v[0:1]
	v_pk_mov_b32 v[74:75], v[0:1], v[0:1]
	v_pk_mov_b32 v[76:77], v[0:1], v[0:1]
	v_pk_mov_b32 v[78:79], v[0:1], v[0:1]
	v_pk_mov_b32 v[88:89], v[0:1], v[0:1]
	v_pk_mov_b32 v[90:91], v[0:1], v[0:1]
	v_pk_mov_b32 v[92:93], v[0:1], v[0:1]
	v_pk_mov_b32 v[94:95], v[0:1], v[0:1]
	v_pk_mov_b32 v[104:105], v[0:1], v[0:1]
	v_pk_mov_b32 v[106:107], v[0:1], v[0:1]
	v_pk_mov_b32 v[108:109], v[0:1], v[0:1]
	v_pk_mov_b32 v[110:111], v[0:1], v[0:1]
	v_pk_mov_b32 v[120:121], v[0:1], v[0:1]
	v_pk_mov_b32 v[122:123], v[0:1], v[0:1]
	v_pk_mov_b32 v[124:125], v[0:1], v[0:1]
	v_pk_mov_b32 v[126:127], v[0:1], v[0:1]
	v_readlane_b32 s98, v252, 5
	s_nop 1
	s_lshl_b32 s98, s98, 5
	s_add_i32 m0, s98, 0x20080
	s_lshl_b32 s98, s52, 14
	s_add_u32 s98, s100, s98
	s_addc_u32 s99, s101, 0
	global_load_lds_dwordx4 v238, s[98:99]
	global_load_lds_dwordx4 v238, s[98:99] offset:1024

; template <class Epi, class Sched, bool ALIGN_EPI = false, bool SP2 = false>
; __device__ __forceinline__ void gemm_phase(PG8_LAS unsigned char* lds, const Gemm g, const Sched& S, const Epi& E, int tid_in) {
;     ...
;         const char* nA = has_next ? (const char*)g.A + (size_t)nxt.pm * tstep : cA; const char* nB = has_next ? (const char*)g.Bt + (size_t)nxt.pn * tstep : cB;
;         for (int t = 0; t < nt; t += 2) {
;             const bool last = (t == nt - 2);
;             const char* a1 = cA + (size_t)(t + 1) * kstep;
;             const char* a2 = last ? nA : cA + (size_t)(t + 2) * kstep; const char* b2 = last ? nB : cB + (size_t)(t + 2) * kstep;
;             const char* a3 = a2 + kstep; const char* b3 = b2 + kstep;
;             if (last && has_next) S.a_ready(nxt);
;             if constexpr (SP2) {
;             PG8_LDB(B0, 0, 0); PG8_LDB(B1, 0, 1); PG8_SCHED; PG8_LDA(At, 0, 0); PG8_STAGE(PG8_SA(1, 1), a1 + hstep, voffA);
;             PG8_WAIT_V(8); PG8_WAIT_L(0); PG8_BAR; PG8_MMA(0, 0, At, B0); PG8_MMA(0, 1, At, B1); PG8_BAR; PG8_SCHED;
;             PG8_LDA(At, 0, 1); PG8_STAGE(PG8_SB(0, 0), b2, voffB); PG8_STAGE(PG8_SB(0, 1), b2 + hstep, voffB); PG8_STAGE(PG8_SA(0, 0), a2, voffA);
;             PG8_WAIT_V(8); PG8_WAIT_L(0); PG8_BAR; PG8_MMA(1, 0, At, B0); PG8_MMA(1, 1, At, B1); PG8_BAR; PG8_SCHED;
;             PG8_LDB(B0, 1, 0); PG8_LDB(B1, 1, 1); PG8_SCHED; PG8_LDA(At, 1, 0); PG8_STAGE(PG8_SA(0, 1), a2 + hstep, voffA);
;             PG8_WAIT_V(8); PG8_WAIT_L(0); PG8_BAR; PG8_MMA(0, 0, At, B0); PG8_MMA(0, 1, At, B1); PG8_BAR; PG8_SCHED;
;             PG8_LDA(At, 1, 1); PG8_STAGE(PG8_SB(1, 0), b3, voffB); PG8_STAGE(PG8_SB(1, 1), b3 + hstep, voffB); PG8_STAGE(PG8_SA(1, 0), a3, voffA);
;             PG8_WAIT_V(8); PG8_WAIT_L(0); PG8_BAR; PG8_MMA(1, 0, At, B0); PG8_MMA(1, 1, At, B1); PG8_BAR; PG8_SCHED;
;             } else {
;             PG8_LDB(B0, 0, 0); PG8_SCHED; PG8_LDA(At, 0, 0); PG8_STAGE(PG8_SA(1, 1), a1 + hstep, voffA);
;             PG8_WAIT_L(8); PG8_BAR; PG8_WAIT_L(0); PG8_MMA(0, 0, At, B0); PG8_BAR; PG8_SCHED;
;             PG8_LDB(B1, 0, 1); PG8_STAGE(PG8_SB(0, 0), b2, voffB);
;             PG8_BAR; PG8_WAIT_L(0); PG8_MMA(0, 1, At, B1); PG8_BAR;
;             PG8_LDA(At, 0, 1); PG8_STAGE(PG8_SA(0, 0), a2, voffA);
;             PG8_BAR; PG8_WAIT_L(0); PG8_MMA(1, 0, At, B0); PG8_BAR; PG8_SCHED;
.LBB0_1503:
	s_ashr_i32 s45, s44, 31
	s_lshl_b64 s[46:47], s[44:45], 19
	s_add_u32 s46, s0, s46
	s_addc_u32 s47, s3, s47
	s_and_b64 s[48:49], s[14:15], exec
	s_cselect_b32 s45, s47, s55
	s_cselect_b32 s51, s46, s54
	s_ashr_i32 s43, s42, 31
	s_lshl_b64 s[48:49], s[42:43], 19
	s_add_u32 s48, s6, s48
	s_addc_u32 s49, s7, s49
	s_and_b64 s[56:57], s[14:15], exec
	s_cselect_b32 s43, s49, s53
	s_cselect_b32 s67, s48, s52
	s_add_u32 s68, s52, 0x100
	s_addc_u32 s69, s53, 0
	s_add_u32 s52, s54, 0x40080
	v_mov_b32_e32 v0, 0
	v_mov_b32_e32 v1, v0
	s_addc_u32 s53, s55, 0
	s_mov_b32 s70, -2
	s_waitcnt lgkmcnt(0)
	v_pk_mov_b32 v[2:3], v[0:1], v[0:1]
	v_pk_mov_b32 v[4:5], v[0:1], v[0:1]
	v_pk_mov_b32 v[6:7], v[0:1], v[0:1]
	v_pk_mov_b32 v[16:17], v[0:1], v[0:1]
	v_pk_mov_b32 v[18:19], v[0:1], v[0:1]
	v_pk_mov_b32 v[20:21], v[0:1], v[0:1]
	v_pk_mov_b32 v[22:23], v[0:1], v[0:1]
	v_pk_mov_b32 v[32:33], v[0:1], v[0:1]
	v_pk_mov_b32 v[34:35], v[0:1], v[0:1]
	v_pk_mov_b32 v[36:37], v[0:1], v[0:1]
	v_pk_mov_b32 v[38:39], v[0:1], v[0:1]
	v_pk_mov_b32 v[48:49], v[0:1], v[0:1]
	v_pk_mov_b32 v[50:51], v[0:1], v[0:1]
	v_pk_mov_b32 v[52:53], v[0:1], v[0:1]
	v_pk_mov_b32 v[54:55], v[0:1], v[0:1]
	v_pk_mov_b32 v[8:9], v[0:1], v[0:1]
	v_pk_mov_b32 v[10:11], v[0:1], v[0:1]
	v_pk_mov_b32 v[12:13], v[0:1], v[0:1]
	v_pk_mov_b32 v[14:15], v[0:1], v[0:1]
	v_pk_mov_b32 v[24:25], v[0:1], v[0:1]
	v_pk_mov_b32 v[26:27], v[0:1], v[0:1]
	v_pk_mov_b32 v[28:29], v[0:1], v[0:1]
	v_pk_mov_b32 v[30:31], v[0:1], v[0:1]
	v_pk_mov_b32 v[40:41], v[0:1], v[0:1]
	v_pk_mov_b32 v[42:43], v[0:1], v[0:1]
	v_pk_mov_b32 v[44:45], v[0:1], v[0:1]
	v_pk_mov_b32 v[46:47], v[0:1], v[0:1]
	v_pk_mov_b32 v[56:57], v[0:1], v[0:1]
	v_pk_mov_b32 v[58:59], v[0:1], v[0:1]
	v_pk_mov_b32 v[60:61], v[0:1], v[0:1]
	v_pk_mov_b32 v[62:63], v[0:1], v[0:1]
	v_pk_mov_b32 v[64:65], v[0:1], v[0:1]
	v_pk_mov_b32 v[66:67], v[0:1], v[0:1]
	v_pk_mov_b32 v[68:69], v[0:1], v[0:1]
	v_pk_mov_b32 v[70:71], v[0:1], v[0:1]
	v_pk_mov_b32 v[80:81], v[0:1], v[0:1]
	v_pk_mov_b32 v[82:83], v[0:1], v[0:1]
	v_pk_mov_b32 v[84:85], v[0:1], v[0:1]
	v_pk_mov_b32 v[86:87], v[0:1], v[0:1]
	v_pk_mov_b32 v[96:97], v[0:1], v[0:1]
	v_pk_mov_b32 v[98:99], v[0:1], v[0:1]
	v_pk_mov_b32 v[100:101], v[0:1], v[0:1]
	v_pk_mov_b32 v[102:103], v[0:1], v[0:1]
	v_pk_mov_b32 v[112:113], v[0:1], v[0:1]
	v_pk_mov_b32 v[114:115], v[0:1], v[0:1]
	v_pk_mov_b32 v[116:117], v[0:1], v[0:1]
	v_pk_mov_b32 v[118:119], v[0:1], v[0:1]
	v_pk_mov_b32 v[72:73], v[0:1], v[0:1]
	v_pk_mov_b32 v[74:75], v[0:1], v[0:1]
	v_pk_mov_b32 v[76:77], v[0:1], v[0:1]
	v_pk_mov_b32 v[78:79], v[0:1], v[0:1]
	v_pk_mov_b32 v[88:89], v[0:1], v[0:1]
	v_pk_mov_b32 v[90:91], v[0:1], v[0:1]
	v_pk_mov_b32 v[92:93], v[0:1], v[0:1]
	v_pk_mov_b32 v[94:95], v[0:1], v[0:1]
	v_pk_mov_b32 v[104:105], v[0:1], v[0:1]
	v_pk_mov_b32 v[106:107], v[0:1], v[0:1]
	v_pk_mov_b32 v[108:109], v[0:1], v[0:1]
	v_pk_mov_b32 v[110:111], v[0:1], v[0:1]
	v_pk_mov_b32 v[124:125], v[0:1], v[0:1]
	v_pk_mov_b32 v[126:127], v[0:1], v[0:1]
	v_pk_mov_b32 v[128:129], v[0:1], v[0:1]
	v_pk_mov_b32 v[130:131], v[0:1], v[0:1]

; template <class Epi, class Sched, bool ALIGN_EPI = false, bool SP2 = false>
; __device__ __forceinline__ void gemm_phase(PG8_LAS unsigned char* lds, const Gemm g, const Sched& S, const Epi& E, int tid_in) {
;     ...
;         const char* nA = has_next ? (const char*)g.A + (size_t)nxt.pm * tstep : cA; const char* nB = has_next ? (const char*)g.Bt + (size_t)nxt.pn * tstep : cB;
;         for (int t = 0; t < nt; t += 2) {
;             const bool last = (t == nt - 2);
;             const char* a1 = cA + (size_t)(t + 1) * kstep;
;             const char* a2 = last ? nA : cA + (size_t)(t + 2) * kstep; const char* b2 = last ? nB : cB + (size_t)(t + 2) * kstep;
;             const char* a3 = a2 + kstep; const char* b3 = b2 + kstep;
;             if (last && has_next) S.a_ready(nxt);
;             if constexpr (SP2) {
;             PG8_LDB(B0, 0, 0); PG8_LDB(B1, 0, 1); PG8_SCHED; PG8_LDA(At, 0, 0); PG8_STAGE(PG8_SA(1, 1), a1 + hstep, voffA);
;             PG8_WAIT_V(8); PG8_WAIT_L(0); PG8_BAR; PG8_MMA(0, 0, At, B0); PG8_MMA(0, 1, At, B1); PG8_BAR; PG8_SCHED;
;             PG8_LDA(At, 0, 1); PG8_STAGE(PG8_SB(0, 0), b2, voffB); PG8_STAGE(PG8_SB(0, 1), b2 + hstep, voffB); PG8_STAGE(PG8_SA(0, 0), a2, voffA);
;             PG8_WAIT_V(8); PG8_WAIT_L(0); PG8_BAR; PG8_MMA(1, 0, At, B0); PG8_MMA(1, 1, At, B1); PG8_BAR; PG8_SCHED;
;             PG8_LDB(B0, 1, 0); PG8_LDB(B1, 1, 1); PG8_SCHED; PG8_LDA(At, 1, 0); PG8_STAGE(PG8_SA(0, 1), a2 + hstep, voffA);
;             PG8_WAIT_V(8); PG8_WAIT_L(0); PG8_BAR; PG8_MMA(0, 0, At, B0); PG8_MMA(0, 1, At, B1); PG8_BAR; PG8_SCHED;
;             PG8_LDA(At, 1, 1); PG8_STAGE(PG8_SB(1, 0), b3, voffB); PG8_STAGE(PG8_SB(1, 1), b3 + hstep, voffB); PG8_STAGE(PG8_SA(1, 0), a3, voffA);
;             PG8_WAIT_V(8); PG8_WAIT_L(0); PG8_BAR; PG8_MMA(1, 0, At, B0); PG8_MMA(1, 1, At, B1); PG8_BAR; PG8_SCHED;
;             } else {
;             PG8_LDB(B0, 0, 0); PG8_SCHED; PG8_LDA(At, 0, 0); PG8_STAGE(PG8_SA(1, 1), a1 + hstep, voffA);
;             PG8_WAIT_L(8); PG8_BAR; PG8_WAIT_L(0); PG8_MMA(0, 0, At, B0); PG8_BAR; PG8_SCHED;
;             PG8_LDB(B1, 0, 1); PG8_STAGE(PG8_SB(0, 0), b2, voffB);
;             PG8_BAR; PG8_WAIT_L(0); PG8_MMA(0, 1, At, B1); PG8_BAR;
;             PG8_LDA(At, 0, 1); PG8_STAGE(PG8_SA(0, 0), a2, voffA);
;             PG8_BAR; PG8_WAIT_L(0); PG8_MMA(1, 0, At, B0); PG8_BAR; PG8_SCHED;
.LBB0_1587:
	s_ashr_i32 s25, s24, 31
	s_lshl_b64 s[26:27], s[24:25], 19
	s_add_u32 s26, s0, s26
	s_addc_u32 s27, s3, s27
	s_and_b64 s[42:43], s[8:9], exec
	s_cselect_b32 s25, s27, s49
	s_cselect_b32 s62, s26, s48
	s_ashr_i32 s23, s22, 31
	s_lshl_b64 s[42:43], s[22:23], 19
	s_add_u32 s42, s6, s42
	s_addc_u32 s43, s7, s43
	s_and_b64 s[50:51], s[8:9], exec
	s_cselect_b32 s23, s43, s47
	s_cselect_b32 s63, s42, s46
	s_add_u32 s64, s46, 0x100
	s_addc_u32 s65, s47, 0
	s_add_u32 s46, s48, 0x40080
	v_mov_b32_e32 v0, 0
	v_mov_b32_e32 v1, v0
	s_addc_u32 s47, s49, 0
	s_mov_b32 s66, -2
	v_pk_mov_b32 v[2:3], v[0:1], v[0:1]
	v_pk_mov_b32 v[4:5], v[0:1], v[0:1]
	v_pk_mov_b32 v[6:7], v[0:1], v[0:1]
	v_pk_mov_b32 v[16:17], v[0:1], v[0:1]
	v_pk_mov_b32 v[18:19], v[0:1], v[0:1]
	v_pk_mov_b32 v[20:21], v[0:1], v[0:1]
	v_pk_mov_b32 v[22:23], v[0:1], v[0:1]
	v_pk_mov_b32 v[32:33], v[0:1], v[0:1]
	v_pk_mov_b32 v[34:35], v[0:1], v[0:1]
	v_pk_mov_b32 v[36:37], v[0:1], v[0:1]
	v_pk_mov_b32 v[38:39], v[0:1], v[0:1]
	v_pk_mov_b32 v[48:49], v[0:1], v[0:1]
	v_pk_mov_b32 v[50:51], v[0:1], v[0:1]
	v_pk_mov_b32 v[52:53], v[0:1], v[0:1]
	v_pk_mov_b32 v[54:55], v[0:1], v[0:1]
	v_pk_mov_b32 v[8:9], v[0:1], v[0:1]
	v_pk_mov_b32 v[10:11], v[0:1], v[0:1]
	v_pk_mov_b32 v[12:13], v[0:1], v[0:1]
	v_pk_mov_b32 v[14:15], v[0:1], v[0:1]
	v_pk_mov_b32 v[24:25], v[0:1], v[0:1]
	v_pk_mov_b32 v[26:27], v[0:1], v[0:1]
	v_pk_mov_b32 v[28:29], v[0:1], v[0:1]
	v_pk_mov_b32 v[30:31], v[0:1], v[0:1]
	v_pk_mov_b32 v[40:41], v[0:1], v[0:1]
	v_pk_mov_b32 v[42:43], v[0:1], v[0:1]
	v_pk_mov_b32 v[44:45], v[0:1], v[0:1]
	v_pk_mov_b32 v[46:47], v[0:1], v[0:1]
	v_pk_mov_b32 v[56:57], v[0:1], v[0:1]
	v_pk_mov_b32 v[58:59], v[0:1], v[0:1]
	v_pk_mov_b32 v[60:61], v[0:1], v[0:1]
	v_pk_mov_b32 v[62:63], v[0:1], v[0:1]
	v_pk_mov_b32 v[64:65], v[0:1], v[0:1]
	v_pk_mov_b32 v[66:67], v[0:1], v[0:1]
	v_pk_mov_b32 v[68:69], v[0:1], v[0:1]
	v_pk_mov_b32 v[70:71], v[0:1], v[0:1]
	v_pk_mov_b32 v[80:81], v[0:1], v[0:1]
	v_pk_mov_b32 v[82:83], v[0:1], v[0:1]
	v_pk_mov_b32 v[84:85], v[0:1], v[0:1]
	v_pk_mov_b32 v[86:87], v[0:1], v[0:1]
	v_pk_mov_b32 v[96:97], v[0:1], v[0:1]
	v_pk_mov_b32 v[98:99], v[0:1], v[0:1]
	v_pk_mov_b32 v[100:101], v[0:1], v[0:1]
	v_pk_mov_b32 v[102:103], v[0:1], v[0:1]
	v_pk_mov_b32 v[112:113], v[0:1], v[0:1]
	v_pk_mov_b32 v[114:115], v[0:1], v[0:1]
	v_pk_mov_b32 v[116:117], v[0:1], v[0:1]
	v_pk_mov_b32 v[118:119], v[0:1], v[0:1]
	v_pk_mov_b32 v[72:73], v[0:1], v[0:1]
	v_pk_mov_b32 v[74:75], v[0:1], v[0:1]
	v_pk_mov_b32 v[76:77], v[0:1], v[0:1]
	v_pk_mov_b32 v[78:79], v[0:1], v[0:1]
	v_pk_mov_b32 v[88:89], v[0:1], v[0:1]
	v_pk_mov_b32 v[90:91], v[0:1], v[0:1]
	v_pk_mov_b32 v[92:93], v[0:1], v[0:1]
	v_pk_mov_b32 v[94:95], v[0:1], v[0:1]
	v_pk_mov_b32 v[104:105], v[0:1], v[0:1]
	v_pk_mov_b32 v[106:107], v[0:1], v[0:1]
	v_pk_mov_b32 v[108:109], v[0:1], v[0:1]
	v_pk_mov_b32 v[110:111], v[0:1], v[0:1]
	v_pk_mov_b32 v[120:121], v[0:1], v[0:1]
	v_pk_mov_b32 v[122:123], v[0:1], v[0:1]
	v_pk_mov_b32 v[124:125], v[0:1], v[0:1]
	v_pk_mov_b32 v[126:127], v[0:1], v[0:1]
	v_readlane_b32 s98, v252, 5
	s_nop 1
	s_lshl_b32 s98, s98, 5
	s_add_i32 m0, s98, 0x20080
	s_lshl_b32 s98, s44, 14
	s_add_u32 s98, s100, s98
	s_addc_u32 s99, s101, 0
	global_load_lds_dwordx4 v238, s[98:99]
	global_load_lds_dwordx4 v238, s[98:99] offset:1024

; template <class Epi, class Sched, bool ALIGN_EPI = false, bool SP2 = false>
; __device__ __forceinline__ void gemm_phase(PG8_LAS unsigned char* lds, const Gemm g, const Sched& S, const Epi& E, int tid_in) {
;     ...
; #pragma unroll
;         for (int a = 0; a < 2; ++a)
; #pragma unroll
;             for (int b = 0; b < 2; ++b)
; #pragma unroll
;                 for (int m = 0; m < 4; ++m)
; #pragma unroll
;                     for (int n = 0; n < 2; ++n) acc[a][b][m][n] = (f32x4){0.f, 0.f, 0.f, 0.f};
;         cur = nxt; cA = nA; cB = nB; ++ui;
.LBB0_1669:
	s_add_u32 s66, s48, 0x100
	v_mov_b32_e32 v0, 0
	v_mov_b32_e32 v1, v0
	s_addc_u32 s67, s49, 0
	s_mov_b32 s68, -2
	s_waitcnt lgkmcnt(0)
	v_pk_mov_b32 v[2:3], v[0:1], v[0:1]
	v_pk_mov_b32 v[4:5], v[0:1], v[0:1]
	v_pk_mov_b32 v[6:7], v[0:1], v[0:1]
	v_pk_mov_b32 v[16:17], v[0:1], v[0:1]
	v_pk_mov_b32 v[18:19], v[0:1], v[0:1]
	v_pk_mov_b32 v[20:21], v[0:1], v[0:1]
	v_pk_mov_b32 v[22:23], v[0:1], v[0:1]
	v_pk_mov_b32 v[32:33], v[0:1], v[0:1]
	v_pk_mov_b32 v[34:35], v[0:1], v[0:1]
	v_pk_mov_b32 v[36:37], v[0:1], v[0:1]
	v_pk_mov_b32 v[38:39], v[0:1], v[0:1]
	v_pk_mov_b32 v[48:49], v[0:1], v[0:1]
	v_pk_mov_b32 v[50:51], v[0:1], v[0:1]
	v_pk_mov_b32 v[52:53], v[0:1], v[0:1]
	v_pk_mov_b32 v[54:55], v[0:1], v[0:1]
	v_pk_mov_b32 v[8:9], v[0:1], v[0:1]
	v_pk_mov_b32 v[10:11], v[0:1], v[0:1]
	v_pk_mov_b32 v[12:13], v[0:1], v[0:1]
	v_pk_mov_b32 v[14:15], v[0:1], v[0:1]
	v_pk_mov_b32 v[24:25], v[0:1], v[0:1]
	v_pk_mov_b32 v[26:27], v[0:1], v[0:1]
	v_pk_mov_b32 v[28:29], v[0:1], v[0:1]
	v_pk_mov_b32 v[30:31], v[0:1], v[0:1]
	v_pk_mov_b32 v[40:41], v[0:1], v[0:1]
	v_pk_mov_b32 v[42:43], v[0:1], v[0:1]
	v_pk_mov_b32 v[44:45], v[0:1], v[0:1]
	v_pk_mov_b32 v[46:47], v[0:1], v[0:1]
	v_pk_mov_b32 v[56:57], v[0:1], v[0:1]
	v_pk_mov_b32 v[58:59], v[0:1], v[0:1]
	v_pk_mov_b32 v[60:61], v[0:1], v[0:1]
	v_pk_mov_b32 v[62:63], v[0:1], v[0:1]
	v_pk_mov_b32 v[64:65], v[0:1], v[0:1]
	v_pk_mov_b32 v[66:67], v[0:1], v[0:1]
	v_pk_mov_b32 v[68:69], v[0:1], v[0:1]
	v_pk_mov_b32 v[70:71], v[0:1], v[0:1]
	v_pk_mov_b32 v[80:81], v[0:1], v[0:1]
	v_pk_mov_b32 v[82:83], v[0:1], v[0:1]
	v_pk_mov_b32 v[84:85], v[0:1], v[0:1]
	v_pk_mov_b32 v[86:87], v[0:1], v[0:1]
	v_pk_mov_b32 v[96:97], v[0:1], v[0:1]
	v_pk_mov_b32 v[98:99], v[0:1], v[0:1]
	v_pk_mov_b32 v[100:101], v[0:1], v[0:1]
	v_pk_mov_b32 v[102:103], v[0:1], v[0:1]
	v_pk_mov_b32 v[112:113], v[0:1], v[0:1]
	v_pk_mov_b32 v[114:115], v[0:1], v[0:1]
	v_pk_mov_b32 v[116:117], v[0:1], v[0:1]
	v_pk_mov_b32 v[118:119], v[0:1], v[0:1]
	v_pk_mov_b32 v[72:73], v[0:1], v[0:1]
	v_pk_mov_b32 v[74:75], v[0:1], v[0:1]
	v_pk_mov_b32 v[76:77], v[0:1], v[0:1]
	v_pk_mov_b32 v[78:79], v[0:1], v[0:1]
	v_pk_mov_b32 v[88:89], v[0:1], v[0:1]
	v_pk_mov_b32 v[90:91], v[0:1], v[0:1]
	v_pk_mov_b32 v[92:93], v[0:1], v[0:1]
	v_pk_mov_b32 v[94:95], v[0:1], v[0:1]
	v_pk_mov_b32 v[104:105], v[0:1], v[0:1]
	v_pk_mov_b32 v[106:107], v[0:1], v[0:1]
	v_pk_mov_b32 v[108:109], v[0:1], v[0:1]
	v_pk_mov_b32 v[110:111], v[0:1], v[0:1]
	v_pk_mov_b32 v[124:125], v[0:1], v[0:1]
	v_pk_mov_b32 v[126:127], v[0:1], v[0:1]
	v_pk_mov_b32 v[128:129], v[0:1], v[0:1]
	v_pk_mov_b32 v[130:131], v[0:1], v[0:1]

;     __device__ bool next(int i, Unit& u) const { if (i > 0) return false; const int t = c - first; if (t < 0 || t >= nM * nN) return false; u.pm = t % nM; u.pn = t / nM; return true; }
; #define PG8_STAGE(bufoff, gbase, voff) do { _Pragma("unroll") for (int _i = 0; _i < 2; ++_i) \
;         __builtin_amdgcn_global_load_lds((const unsigned*)((const char*)(gbase) + (voff)[_i]), (PG8_LAS unsigned*)(lds + (bufoff) + ldsw + _i * 8192), 16, 0, 0); } while (0)
; #define PG8_LDA(dst, b, h) do { _Pragma("unroll") for (int m = 0; m < 4; ++m) _Pragma("unroll") for (int k = 0; k < 2; ++k) dst[m][k] = *(const PG8_LAS bf16x8*)(lds + PG8_SA(b, h) + aoff + m * 2048 + k * 1024); } while (0)
; #define PG8_LDB(dst, b, h) do { _Pragma("unroll") for (int n = 0; n < 2; ++n) _Pragma("unroll") for (int k = 0; k < 2; ++k) dst[n][k] = *(const PG8_LAS bf16x8*)(lds + PG8_SB(b, h) + boff + n * 2048 + k * 1024); } while (0)
; #define PG8_SCHED __builtin_amdgcn_sched_barrier(0)
; template <class Epi, class Sched, bool ALIGN_EPI = false, bool SP2 = false>
; __device__ __forceinline__ void gemm_phase(PG8_LAS unsigned char* lds, const Gemm g, const Sched& S, const Epi& E, int tid_in) {
;     ...
;         const bool has_next = S.next(ui + 1, nxt);
;         const char* nA = has_next ? (const char*)g.A + (size_t)nxt.pm * tstep : cA; const char* nB = has_next ? (const char*)g.Bt + (size_t)nxt.pn * tstep : cB;
;         for (int t = 0; t < nt; t += 2) {
;             const bool last = (t == nt - 2);
;             const char* a1 = cA + (size_t)(t + 1) * kstep;
;             const char* a2 = last ? nA : cA + (size_t)(t + 2) * kstep; const char* b2 = last ? nB : cB + (size_t)(t + 2) * kstep;
;             const char* a3 = a2 + kstep; const char* b3 = b2 + kstep;
;             if (last && has_next) S.a_ready(nxt);
;             if constexpr (SP2) {
;             PG8_LDB(B0, 0, 0); PG8_LDB(B1, 0, 1); PG8_SCHED; PG8_LDA(At, 0, 0); PG8_STAGE(PG8_SA(1, 1), a1 + hstep, voffA);
;     ...
;         for (int a = 0; a < 2; ++a)
; #pragma unroll
;             for (int b = 0; b < 2; ++b)
; #pragma unroll
;                 for (int m = 0; m < 4; ++m)
; #pragma unroll
;                     for (int n = 0; n < 2; ++n) acc[a][b][m][n] = (f32x4){0.f, 0.f, 0.f, 0.f};
.LBB0_1755:
	s_ashr_i32 s25, s24, 31
	s_lshl_b64 s[26:27], s[24:25], 19
	s_add_u32 s26, s12, s26
	s_addc_u32 s27, s13, s27
	s_and_b64 s[42:43], s[6:7], exec
	s_cselect_b32 s9, s27, s49
	s_cselect_b32 s25, s26, s48
	s_ashr_i32 s23, s22, 31
	s_lshl_b64 s[42:43], s[22:23], 19
	s_add_u32 s42, s0, s42
	s_addc_u32 s43, s3, s43
	s_and_b64 s[50:51], s[6:7], exec
	s_cselect_b32 s23, s43, s47
	s_cselect_b32 s69, s42, s46
	s_add_u32 s70, s46, 0x100
	s_addc_u32 s71, s47, 0
	s_add_u32 s46, s48, 0x40080
	v_mov_b32_e32 v0, 0
	v_mov_b32_e32 v1, v0
	s_addc_u32 s47, s49, 0
	s_mov_b32 s72, -2
	v_pk_mov_b32 v[2:3], v[0:1], v[0:1]
	v_pk_mov_b32 v[4:5], v[0:1], v[0:1]
	v_pk_mov_b32 v[6:7], v[0:1], v[0:1]
	v_pk_mov_b32 v[16:17], v[0:1], v[0:1]
	v_pk_mov_b32 v[18:19], v[0:1], v[0:1]
	v_pk_mov_b32 v[20:21], v[0:1], v[0:1]
	v_pk_mov_b32 v[22:23], v[0:1], v[0:1]
	v_pk_mov_b32 v[32:33], v[0:1], v[0:1]
	v_pk_mov_b32 v[34:35], v[0:1], v[0:1]
	v_pk_mov_b32 v[36:37], v[0:1], v[0:1]
	v_pk_mov_b32 v[38:39], v[0:1], v[0:1]
	v_pk_mov_b32 v[48:49], v[0:1], v[0:1]
	v_pk_mov_b32 v[50:51], v[0:1], v[0:1]
	v_pk_mov_b32 v[52:53], v[0:1], v[0:1]
	v_pk_mov_b32 v[54:55], v[0:1], v[0:1]
	v_pk_mov_b32 v[8:9], v[0:1], v[0:1]
	v_pk_mov_b32 v[10:11], v[0:1], v[0:1]
	v_pk_mov_b32 v[12:13], v[0:1], v[0:1]
	v_pk_mov_b32 v[14:15], v[0:1], v[0:1]
	v_pk_mov_b32 v[24:25], v[0:1], v[0:1]
	v_pk_mov_b32 v[26:27], v[0:1], v[0:1]
	v_pk_mov_b32 v[28:29], v[0:1], v[0:1]
	v_pk_mov_b32 v[30:31], v[0:1], v[0:1]
	v_pk_mov_b32 v[40:41], v[0:1], v[0:1]
	v_pk_mov_b32 v[42:43], v[0:1], v[0:1]
	v_pk_mov_b32 v[44:45], v[0:1], v[0:1]
	v_pk_mov_b32 v[46:47], v[0:1], v[0:1]
	v_pk_mov_b32 v[56:57], v[0:1], v[0:1]
	v_pk_mov_b32 v[58:59], v[0:1], v[0:1]
	v_pk_mov_b32 v[60:61], v[0:1], v[0:1]
	v_pk_mov_b32 v[62:63], v[0:1], v[0:1]
	v_pk_mov_b32 v[64:65], v[0:1], v[0:1]
	v_pk_mov_b32 v[66:67], v[0:1], v[0:1]
	v_pk_mov_b32 v[68:69], v[0:1], v[0:1]
	v_pk_mov_b32 v[70:71], v[0:1], v[0:1]
	v_pk_mov_b32 v[80:81], v[0:1], v[0:1]
	v_pk_mov_b32 v[82:83], v[0:1], v[0:1]
	v_pk_mov_b32 v[84:85], v[0:1], v[0:1]
	v_pk_mov_b32 v[86:87], v[0:1], v[0:1]
	v_pk_mov_b32 v[96:97], v[0:1], v[0:1]
	v_pk_mov_b32 v[98:99], v[0:1], v[0:1]
	v_pk_mov_b32 v[100:101], v[0:1], v[0:1]
	v_pk_mov_b32 v[102:103], v[0:1], v[0:1]
	v_pk_mov_b32 v[112:113], v[0:1], v[0:1]
	v_pk_mov_b32 v[114:115], v[0:1], v[0:1]
	v_pk_mov_b32 v[116:117], v[0:1], v[0:1]
	v_pk_mov_b32 v[118:119], v[0:1], v[0:1]
	v_pk_mov_b32 v[72:73], v[0:1], v[0:1]
	v_pk_mov_b32 v[74:75], v[0:1], v[0:1]
	v_pk_mov_b32 v[76:77], v[0:1], v[0:1]
	v_pk_mov_b32 v[78:79], v[0:1], v[0:1]
	v_pk_mov_b32 v[88:89], v[0:1], v[0:1]
	v_pk_mov_b32 v[90:91], v[0:1], v[0:1]
	v_pk_mov_b32 v[92:93], v[0:1], v[0:1]
	v_pk_mov_b32 v[94:95], v[0:1], v[0:1]
	v_pk_mov_b32 v[104:105], v[0:1], v[0:1]
	v_pk_mov_b32 v[106:107], v[0:1], v[0:1]
	v_pk_mov_b32 v[108:109], v[0:1], v[0:1]
	v_pk_mov_b32 v[110:111], v[0:1], v[0:1]
	v_pk_mov_b32 v[120:121], v[0:1], v[0:1]
	v_pk_mov_b32 v[122:123], v[0:1], v[0:1]
	v_pk_mov_b32 v[124:125], v[0:1], v[0:1]
	v_pk_mov_b32 v[126:127], v[0:1], v[0:1]
	v_readlane_b32 s98, v252, 5
	s_nop 1
	s_lshl_b32 s98, s98, 5
	s_add_i32 m0, s98, 0x20080
	s_lshl_b32 s98, s44, 14
	s_add_u32 s98, s100, s98
	s_addc_u32 s99, s101, 0
	global_load_lds_dwordx4 v238, s[98:99]
	global_load_lds_dwordx4 v238, s[98:99] offset:1024

;     __device__ bool next(int i, Unit& u) const { if (i > 0) return false; const int t = c - first; if (t < 0 || t >= nM * nN) return false; u.pm = t % nM; u.pn = t / nM; return true; }
; #define PG8_STAGE(bufoff, gbase, voff) do { _Pragma("unroll") for (int _i = 0; _i < 2; ++_i) \
;         __builtin_amdgcn_global_load_lds((const unsigned*)((const char*)(gbase) + (voff)[_i]), (PG8_LAS unsigned*)(lds + (bufoff) + ldsw + _i * 8192), 16, 0, 0); } while (0)
; #define PG8_LDA(dst, b, h) do { _Pragma("unroll") for (int m = 0; m < 4; ++m) _Pragma("unroll") for (int k = 0; k < 2; ++k) dst[m][k] = *(const PG8_LAS bf16x8*)(lds + PG8_SA(b, h) + aoff + m * 2048 + k * 1024); } while (0)
; #define PG8_LDB(dst, b, h) do { _Pragma("unroll") for (int n = 0; n < 2; ++n) _Pragma("unroll") for (int k = 0; k < 2; ++k) dst[n][k] = *(const PG8_LAS bf16x8*)(lds + PG8_SB(b, h) + boff + n * 2048 + k * 1024); } while (0)
; #define PG8_SCHED __builtin_amdgcn_sched_barrier(0)
; template <class Epi, class Sched, bool ALIGN_EPI = false, bool SP2 = false>
; __device__ __forceinline__ void gemm_phase(PG8_LAS unsigned char* lds, const Gemm g, const Sched& S, const Epi& E, int tid_in) {
;     ...
;         const bool has_next = S.next(ui + 1, nxt);
;         const char* nA = has_next ? (const char*)g.A + (size_t)nxt.pm * tstep : cA; const char* nB = has_next ? (const char*)g.Bt + (size_t)nxt.pn * tstep : cB;
;         for (int t = 0; t < nt; t += 2) {
;             const bool last = (t == nt - 2);
;             const char* a1 = cA + (size_t)(t + 1) * kstep;
;             const char* a2 = last ? nA : cA + (size_t)(t + 2) * kstep; const char* b2 = last ? nB : cB + (size_t)(t + 2) * kstep;
;             const char* a3 = a2 + kstep; const char* b3 = b2 + kstep;
;             if (last && has_next) S.a_ready(nxt);
;             if constexpr (SP2) {
;             PG8_LDB(B0, 0, 0); PG8_LDB(B1, 0, 1); PG8_SCHED; PG8_LDA(At, 0, 0); PG8_STAGE(PG8_SA(1, 1), a1 + hstep, voffA);
;     ...
;         for (int a = 0; a < 2; ++a)
; #pragma unroll
;             for (int b = 0; b < 2; ++b)
; #pragma unroll
;                 for (int m = 0; m < 4; ++m)
; #pragma unroll
;                     for (int n = 0; n < 2; ++n) acc[a][b][m][n] = (f32x4){0.f, 0.f, 0.f, 0.f};
.LBB0_1955:
	s_ashr_i32 s27, s26, 31
	s_lshl_b64 s[34:35], s[26:27], 19
	s_add_u32 s34, s0, s34
	s_addc_u32 s35, s1, s35
	s_and_b64 s[36:37], s[8:9], exec
	s_cselect_b32 s27, s35, s43
	s_cselect_b32 s39, s34, s42
	s_ashr_i32 s25, s24, 31
	s_lshl_b64 s[36:37], s[24:25], 19
	s_add_u32 s36, s3, s36
	s_addc_u32 s37, s4, s37
	s_and_b64 s[44:45], s[8:9], exec
	s_cselect_b32 s25, s37, s41
	s_cselect_b32 s54, s36, s40
	s_add_u32 s55, s40, 0x100
	s_addc_u32 s56, s41, 0
	s_add_u32 s40, s42, 0x40080
	v_mov_b32_e32 v0, 0
	v_mov_b32_e32 v1, v0
	s_addc_u32 s41, s43, 0
	s_mov_b32 s57, -2
	s_waitcnt lgkmcnt(0)
	v_pk_mov_b32 v[2:3], v[0:1], v[0:1]
	v_pk_mov_b32 v[4:5], v[0:1], v[0:1]
	v_pk_mov_b32 v[6:7], v[0:1], v[0:1]
	v_pk_mov_b32 v[16:17], v[0:1], v[0:1]
	v_pk_mov_b32 v[18:19], v[0:1], v[0:1]
	v_pk_mov_b32 v[20:21], v[0:1], v[0:1]
	v_pk_mov_b32 v[22:23], v[0:1], v[0:1]
	v_pk_mov_b32 v[32:33], v[0:1], v[0:1]
	v_pk_mov_b32 v[34:35], v[0:1], v[0:1]
	v_pk_mov_b32 v[36:37], v[0:1], v[0:1]
	v_pk_mov_b32 v[38:39], v[0:1], v[0:1]
	v_pk_mov_b32 v[48:49], v[0:1], v[0:1]
	v_pk_mov_b32 v[50:51], v[0:1], v[0:1]
	v_pk_mov_b32 v[52:53], v[0:1], v[0:1]
	v_pk_mov_b32 v[54:55], v[0:1], v[0:1]
	v_pk_mov_b32 v[8:9], v[0:1], v[0:1]
	v_pk_mov_b32 v[10:11], v[0:1], v[0:1]
	v_pk_mov_b32 v[12:13], v[0:1], v[0:1]
	v_pk_mov_b32 v[14:15], v[0:1], v[0:1]
	v_pk_mov_b32 v[24:25], v[0:1], v[0:1]
	v_pk_mov_b32 v[26:27], v[0:1], v[0:1]
	v_pk_mov_b32 v[28:29], v[0:1], v[0:1]
	v_pk_mov_b32 v[30:31], v[0:1], v[0:1]
	v_pk_mov_b32 v[40:41], v[0:1], v[0:1]
	v_pk_mov_b32 v[42:43], v[0:1], v[0:1]
	v_pk_mov_b32 v[44:45], v[0:1], v[0:1]
	v_pk_mov_b32 v[46:47], v[0:1], v[0:1]
	v_pk_mov_b32 v[56:57], v[0:1], v[0:1]
	v_pk_mov_b32 v[58:59], v[0:1], v[0:1]
	v_pk_mov_b32 v[60:61], v[0:1], v[0:1]
	v_pk_mov_b32 v[62:63], v[0:1], v[0:1]
	v_pk_mov_b32 v[64:65], v[0:1], v[0:1]
	v_pk_mov_b32 v[66:67], v[0:1], v[0:1]
	v_pk_mov_b32 v[68:69], v[0:1], v[0:1]
	v_pk_mov_b32 v[70:71], v[0:1], v[0:1]
	v_pk_mov_b32 v[80:81], v[0:1], v[0:1]
	v_pk_mov_b32 v[82:83], v[0:1], v[0:1]
	v_pk_mov_b32 v[84:85], v[0:1], v[0:1]
	v_pk_mov_b32 v[86:87], v[0:1], v[0:1]
	v_pk_mov_b32 v[96:97], v[0:1], v[0:1]
	v_pk_mov_b32 v[98:99], v[0:1], v[0:1]
	v_pk_mov_b32 v[100:101], v[0:1], v[0:1]
	v_pk_mov_b32 v[102:103], v[0:1], v[0:1]
	v_pk_mov_b32 v[112:113], v[0:1], v[0:1]
	v_pk_mov_b32 v[114:115], v[0:1], v[0:1]
	v_pk_mov_b32 v[116:117], v[0:1], v[0:1]
	v_pk_mov_b32 v[118:119], v[0:1], v[0:1]
	v_pk_mov_b32 v[72:73], v[0:1], v[0:1]
	v_pk_mov_b32 v[74:75], v[0:1], v[0:1]
	v_pk_mov_b32 v[76:77], v[0:1], v[0:1]
	v_pk_mov_b32 v[78:79], v[0:1], v[0:1]
	v_pk_mov_b32 v[88:89], v[0:1], v[0:1]
	v_pk_mov_b32 v[90:91], v[0:1], v[0:1]
	v_pk_mov_b32 v[92:93], v[0:1], v[0:1]
	v_pk_mov_b32 v[94:95], v[0:1], v[0:1]
	v_pk_mov_b32 v[104:105], v[0:1], v[0:1]
	v_pk_mov_b32 v[106:107], v[0:1], v[0:1]
	v_pk_mov_b32 v[108:109], v[0:1], v[0:1]
	v_pk_mov_b32 v[110:111], v[0:1], v[0:1]
	v_pk_mov_b32 v[120:121], v[0:1], v[0:1]
	v_pk_mov_b32 v[122:123], v[0:1], v[0:1]
	v_pk_mov_b32 v[124:125], v[0:1], v[0:1]
	v_pk_mov_b32 v[126:127], v[0:1], v[0:1]

;     __device__ bool next(int i, Unit& u) const { if (i > 0) return false; const int t = c - first; if (t < 0 || t >= nM * nN) return false; u.pm = t % nM; u.pn = t / nM; return true; }
; #define PG8_STAGE(bufoff, gbase, voff) do { _Pragma("unroll") for (int _i = 0; _i < 2; ++_i) \
;         __builtin_amdgcn_global_load_lds((const unsigned*)((const char*)(gbase) + (voff)[_i]), (PG8_LAS unsigned*)(lds + (bufoff) + ldsw + _i * 8192), 16, 0, 0); } while (0)
; #define PG8_LDA(dst, b, h) do { _Pragma("unroll") for (int m = 0; m < 4; ++m) _Pragma("unroll") for (int k = 0; k < 2; ++k) dst[m][k] = *(const PG8_LAS bf16x8*)(lds + PG8_SA(b, h) + aoff + m * 2048 + k * 1024); } while (0)
; #define PG8_LDB(dst, b, h) do { _Pragma("unroll") for (int n = 0; n < 2; ++n) _Pragma("unroll") for (int k = 0; k < 2; ++k) dst[n][k] = *(const PG8_LAS bf16x8*)(lds + PG8_SB(b, h) + boff + n * 2048 + k * 1024); } while (0)
; #define PG8_SCHED __builtin_amdgcn_sched_barrier(0)
; template <class Epi, class Sched, bool ALIGN_EPI = false, bool SP2 = false>
; __device__ __forceinline__ void gemm_phase(PG8_LAS unsigned char* lds, const Gemm g, const Sched& S, const Epi& E, int tid_in) {
;     ...
;         const bool has_next = S.next(ui + 1, nxt);
;         const char* nA = has_next ? (const char*)g.A + (size_t)nxt.pm * tstep : cA; const char* nB = has_next ? (const char*)g.Bt + (size_t)nxt.pn * tstep : cB;
;         for (int t = 0; t < nt; t += 2) {
;             const bool last = (t == nt - 2);
;             const char* a1 = cA + (size_t)(t + 1) * kstep;
;             const char* a2 = last ? nA : cA + (size_t)(t + 2) * kstep; const char* b2 = last ? nB : cB + (size_t)(t + 2) * kstep;
;             const char* a3 = a2 + kstep; const char* b3 = b2 + kstep;
;             if (last && has_next) S.a_ready(nxt);
;             if constexpr (SP2) {
;             PG8_LDB(B0, 0, 0); PG8_LDB(B1, 0, 1); PG8_SCHED; PG8_LDA(At, 0, 0); PG8_STAGE(PG8_SA(1, 1), a1 + hstep, voffA);
;     ...
;         for (int a = 0; a < 2; ++a)
; #pragma unroll
;             for (int b = 0; b < 2; ++b)
; #pragma unroll
;                 for (int m = 0; m < 4; ++m)
; #pragma unroll
;                     for (int n = 0; n < 2; ++n) acc[a][b][m][n] = (f32x4){0.f, 0.f, 0.f, 0.f};
.LBB0_2039:
	s_ashr_i32 s19, s18, 31
	s_lshl_b64 s[20:21], s[18:19], 19
	s_add_u32 s20, s0, s20
	s_addc_u32 s21, s1, s21
	s_and_b64 s[22:23], s[6:7], exec
	s_cselect_b32 s19, s21, s35
	s_cselect_b32 s49, s20, s34
	s_ashr_i32 s17, s16, 31
	s_lshl_b64 s[22:23], s[16:17], 19
	s_add_u32 s22, s3, s22
	s_addc_u32 s23, s4, s23
	s_and_b64 s[36:37], s[6:7], exec
	s_cselect_b32 s17, s23, s27
	s_cselect_b32 s50, s22, s26
	s_add_u32 s51, s26, 0x100
	s_addc_u32 s52, s27, 0
	s_add_u32 s26, s34, 0x40080
	v_mov_b32_e32 v0, 0
	v_mov_b32_e32 v1, v0
	s_addc_u32 s27, s35, 0
	s_mov_b32 s53, -2
	v_pk_mov_b32 v[2:3], v[0:1], v[0:1]
	v_pk_mov_b32 v[4:5], v[0:1], v[0:1]
	v_pk_mov_b32 v[6:7], v[0:1], v[0:1]
	v_pk_mov_b32 v[16:17], v[0:1], v[0:1]
	v_pk_mov_b32 v[18:19], v[0:1], v[0:1]
	v_pk_mov_b32 v[20:21], v[0:1], v[0:1]
	v_pk_mov_b32 v[22:23], v[0:1], v[0:1]
	v_pk_mov_b32 v[32:33], v[0:1], v[0:1]
	v_pk_mov_b32 v[34:35], v[0:1], v[0:1]
	v_pk_mov_b32 v[36:37], v[0:1], v[0:1]
	v_pk_mov_b32 v[38:39], v[0:1], v[0:1]
	v_pk_mov_b32 v[48:49], v[0:1], v[0:1]
	v_pk_mov_b32 v[50:51], v[0:1], v[0:1]
	v_pk_mov_b32 v[52:53], v[0:1], v[0:1]
	v_pk_mov_b32 v[54:55], v[0:1], v[0:1]
	v_pk_mov_b32 v[8:9], v[0:1], v[0:1]
	v_pk_mov_b32 v[10:11], v[0:1], v[0:1]
	v_pk_mov_b32 v[12:13], v[0:1], v[0:1]
	v_pk_mov_b32 v[14:15], v[0:1], v[0:1]
	v_pk_mov_b32 v[24:25], v[0:1], v[0:1]
	v_pk_mov_b32 v[26:27], v[0:1], v[0:1]
	v_pk_mov_b32 v[28:29], v[0:1], v[0:1]
	v_pk_mov_b32 v[30:31], v[0:1], v[0:1]
	v_pk_mov_b32 v[40:41], v[0:1], v[0:1]
	v_pk_mov_b32 v[42:43], v[0:1], v[0:1]
	v_pk_mov_b32 v[44:45], v[0:1], v[0:1]
	v_pk_mov_b32 v[46:47], v[0:1], v[0:1]
	v_pk_mov_b32 v[56:57], v[0:1], v[0:1]
	v_pk_mov_b32 v[58:59], v[0:1], v[0:1]
	v_pk_mov_b32 v[60:61], v[0:1], v[0:1]
	v_pk_mov_b32 v[62:63], v[0:1], v[0:1]
	v_pk_mov_b32 v[64:65], v[0:1], v[0:1]
	v_pk_mov_b32 v[66:67], v[0:1], v[0:1]
	v_pk_mov_b32 v[68:69], v[0:1], v[0:1]
	v_pk_mov_b32 v[70:71], v[0:1], v[0:1]
	v_pk_mov_b32 v[80:81], v[0:1], v[0:1]
	v_pk_mov_b32 v[82:83], v[0:1], v[0:1]
	v_pk_mov_b32 v[84:85], v[0:1], v[0:1]
	v_pk_mov_b32 v[86:87], v[0:1], v[0:1]
	v_pk_mov_b32 v[96:97], v[0:1], v[0:1]
	v_pk_mov_b32 v[98:99], v[0:1], v[0:1]
	v_pk_mov_b32 v[100:101], v[0:1], v[0:1]
	v_pk_mov_b32 v[102:103], v[0:1], v[0:1]
	v_pk_mov_b32 v[112:113], v[0:1], v[0:1]
	v_pk_mov_b32 v[114:115], v[0:1], v[0:1]
	v_pk_mov_b32 v[116:117], v[0:1], v[0:1]
	v_pk_mov_b32 v[118:119], v[0:1], v[0:1]
	v_pk_mov_b32 v[72:73], v[0:1], v[0:1]
	v_pk_mov_b32 v[74:75], v[0:1], v[0:1]
	v_pk_mov_b32 v[76:77], v[0:1], v[0:1]
	v_pk_mov_b32 v[78:79], v[0:1], v[0:1]
	v_pk_mov_b32 v[88:89], v[0:1], v[0:1]
	v_pk_mov_b32 v[90:91], v[0:1], v[0:1]
	v_pk_mov_b32 v[92:93], v[0:1], v[0:1]
	v_pk_mov_b32 v[94:95], v[0:1], v[0:1]
	v_pk_mov_b32 v[104:105], v[0:1], v[0:1]
	v_pk_mov_b32 v[106:107], v[0:1], v[0:1]
	v_pk_mov_b32 v[108:109], v[0:1], v[0:1]
	v_pk_mov_b32 v[110:111], v[0:1], v[0:1]
	v_pk_mov_b32 v[120:121], v[0:1], v[0:1]
	v_pk_mov_b32 v[122:123], v[0:1], v[0:1]
	v_pk_mov_b32 v[124:125], v[0:1], v[0:1]
	v_pk_mov_b32 v[126:127], v[0:1], v[0:1]
	v_readlane_b32 s98, v252, 5
	s_nop 1
	s_lshl_b32 s98, s98, 5
	s_add_i32 m0, s98, 0x20080
	s_lshl_b32 s98, s24, 14
	s_add_u32 s98, s100, s98
	s_addc_u32 s99, s101, 0
	global_load_lds_dwordx4 v238, s[98:99]
	global_load_lds_dwordx4 v238, s[98:99] offset:1024

; template <class Epi, class Sched, bool ALIGN_EPI = false, bool SP2 = false>
; __device__ __forceinline__ void gemm_phase(PG8_LAS unsigned char* lds, const Gemm g, const Sched& S, const Epi& E, int tid_in) {
;     ...
;         for (int a = 0; a < 2; ++a)
; #pragma unroll
;             for (int b = 0; b < 2; ++b)
; #pragma unroll
;                 for (int m = 0; m < 4; ++m)
; #pragma unroll
;                     for (int n = 0; n < 2; ++n) acc[a][b][m][n] = (f32x4){0.f, 0.f, 0.f, 0.f};
.LBB0_2119:
	s_add_u32 s47, s20, 0x100
	v_mov_b32_e32 v0, 0
	v_mov_b32_e32 v1, v0
	s_addc_u32 s48, s21, 0
	s_mov_b32 s49, -2
	v_pk_mov_b32 v[2:3], v[0:1], v[0:1]
	v_pk_mov_b32 v[4:5], v[0:1], v[0:1]
	v_pk_mov_b32 v[6:7], v[0:1], v[0:1]
	v_pk_mov_b32 v[12:13], v[0:1], v[0:1]
	v_pk_mov_b32 v[14:15], v[0:1], v[0:1]
	v_pk_mov_b32 v[20:21], v[0:1], v[0:1]
	v_pk_mov_b32 v[22:23], v[0:1], v[0:1]
	v_pk_mov_b32 v[28:29], v[0:1], v[0:1]
	v_pk_mov_b32 v[30:31], v[0:1], v[0:1]
	v_pk_mov_b32 v[36:37], v[0:1], v[0:1]
	v_pk_mov_b32 v[38:39], v[0:1], v[0:1]
	v_pk_mov_b32 v[44:45], v[0:1], v[0:1]
	v_pk_mov_b32 v[46:47], v[0:1], v[0:1]
	v_pk_mov_b32 v[52:53], v[0:1], v[0:1]
	v_pk_mov_b32 v[54:55], v[0:1], v[0:1]
	v_pk_mov_b32 v[8:9], v[0:1], v[0:1]
	v_pk_mov_b32 v[10:11], v[0:1], v[0:1]
	v_pk_mov_b32 v[16:17], v[0:1], v[0:1]
	v_pk_mov_b32 v[18:19], v[0:1], v[0:1]
	v_pk_mov_b32 v[24:25], v[0:1], v[0:1]
	v_pk_mov_b32 v[26:27], v[0:1], v[0:1]
	v_pk_mov_b32 v[32:33], v[0:1], v[0:1]
	v_pk_mov_b32 v[34:35], v[0:1], v[0:1]
	v_pk_mov_b32 v[40:41], v[0:1], v[0:1]
	v_pk_mov_b32 v[42:43], v[0:1], v[0:1]
	v_pk_mov_b32 v[48:49], v[0:1], v[0:1]
	v_pk_mov_b32 v[50:51], v[0:1], v[0:1]
	v_pk_mov_b32 v[56:57], v[0:1], v[0:1]
	v_pk_mov_b32 v[58:59], v[0:1], v[0:1]
	v_pk_mov_b32 v[60:61], v[0:1], v[0:1]
	v_pk_mov_b32 v[62:63], v[0:1], v[0:1]
	v_pk_mov_b32 v[64:65], v[0:1], v[0:1]
	v_pk_mov_b32 v[66:67], v[0:1], v[0:1]
	v_pk_mov_b32 v[68:69], v[0:1], v[0:1]
	v_pk_mov_b32 v[70:71], v[0:1], v[0:1]
	v_pk_mov_b32 v[76:77], v[0:1], v[0:1]
	v_pk_mov_b32 v[78:79], v[0:1], v[0:1]
	v_pk_mov_b32 v[84:85], v[0:1], v[0:1]
	v_pk_mov_b32 v[86:87], v[0:1], v[0:1]
	v_pk_mov_b32 v[92:93], v[0:1], v[0:1]
	v_pk_mov_b32 v[94:95], v[0:1], v[0:1]
	v_pk_mov_b32 v[100:101], v[0:1], v[0:1]
	v_pk_mov_b32 v[102:103], v[0:1], v[0:1]
	v_pk_mov_b32 v[112:113], v[0:1], v[0:1]
	v_pk_mov_b32 v[114:115], v[0:1], v[0:1]
	v_pk_mov_b32 v[116:117], v[0:1], v[0:1]
	v_pk_mov_b32 v[118:119], v[0:1], v[0:1]
	v_pk_mov_b32 v[72:73], v[0:1], v[0:1]
	v_pk_mov_b32 v[74:75], v[0:1], v[0:1]
	v_pk_mov_b32 v[80:81], v[0:1], v[0:1]
	v_pk_mov_b32 v[82:83], v[0:1], v[0:1]
	v_pk_mov_b32 v[88:89], v[0:1], v[0:1]
	v_pk_mov_b32 v[90:91], v[0:1], v[0:1]
	v_pk_mov_b32 v[96:97], v[0:1], v[0:1]
	v_pk_mov_b32 v[98:99], v[0:1], v[0:1]
	v_pk_mov_b32 v[104:105], v[0:1], v[0:1]
	v_pk_mov_b32 v[106:107], v[0:1], v[0:1]
	v_pk_mov_b32 v[108:109], v[0:1], v[0:1]
	v_pk_mov_b32 v[110:111], v[0:1], v[0:1]
	v_pk_mov_b32 v[120:121], v[0:1], v[0:1]
	v_pk_mov_b32 v[122:123], v[0:1], v[0:1]
	v_pk_mov_b32 v[124:125], v[0:1], v[0:1]
	v_pk_mov_b32 v[126:127], v[0:1], v[0:1]
